# K-loop LDS-DMA issue rebalanced 2+6 -> 4+4 per super-phase in six GEMM instances (one B stage moved to the next SP1 load segment, waits re-derived 8/6/8/6)
# baseline (speedup 1.0000x reference)
.LBB0_226:
	s_add_u32 s98, s49, 0x3ff80
	s_addc_u32 s99, s50, 0
	ds_read_b128 v[156:159], v152
	ds_read_b128 v[160:163], v152 offset:1024
	ds_read_b128 v[164:167], v152 offset:2048
	ds_read_b128 v[168:171], v152 offset:3072
	ds_read_b128 v[172:175], v153
	ds_read_b128 v[176:179], v153 offset:1024
	ds_read_b128 v[180:183], v153 offset:2048
	ds_read_b128 v[186:189], v153 offset:3072
	s_add_u32 s24, s22, 0xfffc0080
	s_addc_u32 s25, s23, -1
	s_cmp_eq_u32 s51, 12
	s_cselect_b32 s27, s15, s25
	s_cselect_b32 s26, s46, s24
	s_cselect_b32 s25, s13, s50
	s_cselect_b32 s24, s47, s49
	v_lshl_add_u64 v[148:149], s[98:99], 0, v[130:131]
	s_add_i32 m0, s30, 0x1c000
	s_nop 0
	global_load_lds_dwordx4 v[148:149], off
	v_lshl_add_u64 v[148:149], s[98:99], 0, v[134:135]
	s_add_i32 m0, s30, 0x1e000
	s_nop 0
	global_load_lds_dwordx4 v[148:149], off
	v_lshl_add_u64 v[148:149], s[22:23], 0, v[138:139]
	s_add_i32 m0, s21, 0xc000
	ds_read_b128 v[192:195], v154
	ds_read_b128 v[196:199], v154 offset:1024
	ds_read_b128 v[200:203], v154 offset:2048
	ds_read_b128 v[204:207], v154 offset:3072
	ds_read_b128 v[208:211], v154 offset:4096
	ds_read_b128 v[212:215], v154 offset:5120
	ds_read_b128 v[216:219], v154 offset:6144
	ds_read_b128 v[220:223], v154 offset:7168
	global_load_lds_dwordx4 v[148:149], off
	v_lshl_add_u64 v[148:149], s[22:23], 0, v[140:141]
	s_add_i32 m0, s21, 0xe000
	s_nop 0
	global_load_lds_dwordx4 v[148:149], off
	s_waitcnt vmcnt(8)
	s_waitcnt lgkmcnt(0)
	s_barrier
	s_setprio 1
	s_waitcnt lgkmcnt(0)
	v_mfma_f32_16x16x32_bf16 v[124:127], v[156:159], v[192:195], v[124:127]
	v_mfma_f32_16x16x32_bf16 v[120:123], v[164:167], v[192:195], v[120:123]
	v_mfma_f32_16x16x32_bf16 v[112:115], v[156:159], v[200:203], v[112:115]
	v_mfma_f32_16x16x32_bf16 v[104:107], v[164:167], v[200:203], v[104:107]
	v_mfma_f32_16x16x32_bf16 v[96:99], v[156:159], v[208:211], v[96:99]
	v_mfma_f32_16x16x32_bf16 v[88:91], v[164:167], v[208:211], v[88:91]
	v_mfma_f32_16x16x32_bf16 v[80:83], v[156:159], v[216:219], v[80:83]
	v_mfma_f32_16x16x32_bf16 v[72:75], v[164:167], v[216:219], v[72:75]
	v_mfma_f32_16x16x32_bf16 v[124:127], v[160:163], v[196:199], v[124:127]
	v_mfma_f32_16x16x32_bf16 v[120:123], v[168:171], v[196:199], v[120:123]
	v_mfma_f32_16x16x32_bf16 v[112:115], v[160:163], v[204:207], v[112:115]
	v_mfma_f32_16x16x32_bf16 v[104:107], v[168:171], v[204:207], v[104:107]
	v_mfma_f32_16x16x32_bf16 v[96:99], v[160:163], v[212:215], v[96:99]
	v_mfma_f32_16x16x32_bf16 v[88:91], v[168:171], v[212:215], v[88:91]
	v_mfma_f32_16x16x32_bf16 v[80:83], v[160:163], v[220:223], v[80:83]
	v_mfma_f32_16x16x32_bf16 v[72:75], v[168:171], v[220:223], v[72:75]
	s_setprio 0
	s_setprio 1
	v_mfma_f32_16x16x32_bf16 v[116:119], v[172:175], v[192:195], v[116:119]
	v_mfma_f32_16x16x32_bf16 v[108:111], v[180:183], v[192:195], v[108:111]
	v_mfma_f32_16x16x32_bf16 v[100:103], v[172:175], v[200:203], v[100:103]
	v_mfma_f32_16x16x32_bf16 v[92:95], v[180:183], v[200:203], v[92:95]
	v_mfma_f32_16x16x32_bf16 v[84:87], v[172:175], v[208:211], v[84:87]
	v_mfma_f32_16x16x32_bf16 v[76:79], v[180:183], v[208:211], v[76:79]
	v_mfma_f32_16x16x32_bf16 v[68:71], v[172:175], v[216:219], v[68:71]
	v_mfma_f32_16x16x32_bf16 v[64:67], v[180:183], v[216:219], v[64:67]
	v_mfma_f32_16x16x32_bf16 v[116:119], v[176:179], v[196:199], v[116:119]
	v_mfma_f32_16x16x32_bf16 v[108:111], v[186:189], v[196:199], v[108:111]
	v_mfma_f32_16x16x32_bf16 v[100:103], v[176:179], v[204:207], v[100:103]
	v_mfma_f32_16x16x32_bf16 v[92:95], v[186:189], v[204:207], v[92:95]
	v_mfma_f32_16x16x32_bf16 v[84:87], v[176:179], v[212:215], v[84:87]
	v_mfma_f32_16x16x32_bf16 v[76:79], v[186:189], v[212:215], v[76:79]
	v_mfma_f32_16x16x32_bf16 v[68:71], v[176:179], v[220:223], v[68:71]
	v_mfma_f32_16x16x32_bf16 v[64:67], v[186:189], v[220:223], v[64:67]
	s_setprio 0
	s_barrier
	s_add_i32 s52, s41, s30
	v_lshl_add_u64 v[148:149], s[24:25], 0, v[130:131]
	s_mov_b32 m0, s52
	ds_read_b128 v[192:195], v154 offset:16384
	ds_read_b128 v[196:199], v154 offset:17408
	ds_read_b128 v[200:203], v154 offset:18432
	ds_read_b128 v[204:207], v154 offset:19456
	ds_read_b128 v[208:211], v154 offset:20480
	ds_read_b128 v[212:215], v154 offset:21504
	ds_read_b128 v[216:219], v154 offset:22528
	ds_read_b128 v[220:223], v154 offset:23552
	global_load_lds_dwordx4 v[148:149], off
	s_add_i32 m0, s52, 0x2000
	s_add_u32 s52, s24, 0x40000
	v_lshl_add_u64 v[224:225], s[24:25], 0, v[134:135]
	s_addc_u32 s53, s25, 0
	s_add_i32 s54, s42, s30
	global_load_lds_dwordx4 v[224:225], off
	v_lshl_add_u64 v[226:227], s[52:53], 0, v[130:131]
	s_mov_b32 m0, s54
	v_lshl_add_u64 v[228:229], s[26:27], 0, v[132:133]
	s_nop 0
	v_lshl_add_u64 v[226:227], s[52:53], 0, v[134:135]
	s_add_i32 m0, s54, 0x2000
	s_nop 0
	s_nop 0
	v_lshl_add_u64 v[226:227], s[26:27], 0, v[128:129]
	s_mov_b32 m0, s21
	s_nop 0
	global_load_lds_dwordx4 v[226:227], off
	s_mov_b32 m0, s34
	s_nop 0
	global_load_lds_dwordx4 v[228:229], off
	s_waitcnt vmcnt(6)
	s_waitcnt lgkmcnt(0)
	s_barrier
	s_setprio 1
	s_waitcnt lgkmcnt(0)
	v_mfma_f32_16x16x32_bf16 v[60:63], v[156:159], v[192:195], v[60:63]
	v_mfma_f32_16x16x32_bf16 v[56:59], v[164:167], v[192:195], v[56:59]
	v_mfma_f32_16x16x32_bf16 v[48:51], v[156:159], v[200:203], v[48:51]
	v_mfma_f32_16x16x32_bf16 v[40:43], v[164:167], v[200:203], v[40:43]
	v_mfma_f32_16x16x32_bf16 v[32:35], v[156:159], v[208:211], v[32:35]
	v_mfma_f32_16x16x32_bf16 v[24:27], v[164:167], v[208:211], v[24:27]
	v_mfma_f32_16x16x32_bf16 v[16:19], v[156:159], v[216:219], v[16:19]
	v_mfma_f32_16x16x32_bf16 v[8:11], v[164:167], v[216:219], v[8:11]
	v_mfma_f32_16x16x32_bf16 v[60:63], v[160:163], v[196:199], v[60:63]
	v_mfma_f32_16x16x32_bf16 v[56:59], v[168:171], v[196:199], v[56:59]
	v_mfma_f32_16x16x32_bf16 v[48:51], v[160:163], v[204:207], v[48:51]
	v_mfma_f32_16x16x32_bf16 v[40:43], v[168:171], v[204:207], v[40:43]
	v_mfma_f32_16x16x32_bf16 v[32:35], v[160:163], v[212:215], v[32:35]
	v_mfma_f32_16x16x32_bf16 v[24:27], v[168:171], v[212:215], v[24:27]
	v_mfma_f32_16x16x32_bf16 v[16:19], v[160:163], v[220:223], v[16:19]
	v_mfma_f32_16x16x32_bf16 v[8:11], v[168:171], v[220:223], v[8:11]
	s_setprio 0
	s_setprio 1
	v_mfma_f32_16x16x32_bf16 v[52:55], v[172:175], v[192:195], v[52:55]
	v_mfma_f32_16x16x32_bf16 v[44:47], v[180:183], v[192:195], v[44:47]
	v_mfma_f32_16x16x32_bf16 v[36:39], v[172:175], v[200:203], v[36:39]
	v_mfma_f32_16x16x32_bf16 v[28:31], v[180:183], v[200:203], v[28:31]
	v_mfma_f32_16x16x32_bf16 v[20:23], v[172:175], v[208:211], v[20:23]
	v_mfma_f32_16x16x32_bf16 v[12:15], v[180:183], v[208:211], v[12:15]
	v_mfma_f32_16x16x32_bf16 v[4:7], v[172:175], v[216:219], v[4:7]
	v_mfma_f32_16x16x32_bf16 v[0:3], v[180:183], v[216:219], v[0:3]
	v_mfma_f32_16x16x32_bf16 v[52:55], v[176:179], v[196:199], v[52:55]
	v_mfma_f32_16x16x32_bf16 v[44:47], v[186:189], v[196:199], v[44:47]
	v_mfma_f32_16x16x32_bf16 v[36:39], v[176:179], v[204:207], v[36:39]
	v_mfma_f32_16x16x32_bf16 v[28:31], v[186:189], v[204:207], v[28:31]
	v_mfma_f32_16x16x32_bf16 v[20:23], v[176:179], v[212:215], v[20:23]
	v_mfma_f32_16x16x32_bf16 v[12:15], v[186:189], v[212:215], v[12:15]
	v_mfma_f32_16x16x32_bf16 v[4:7], v[176:179], v[220:223], v[4:7]
	v_mfma_f32_16x16x32_bf16 v[0:3], v[186:189], v[220:223], v[0:3]
	s_setprio 0
	s_barrier
	s_add_u32 s98, s24, 0x40000
	s_addc_u32 s99, s25, 0
	s_add_i32 s52, 0, 0x18000
	v_add_u32_e32 v136, s52, v150
	s_add_i32 s53, 0, 0x1c000
	ds_read_b128 v[156:159], v136
	ds_read_b128 v[160:163], v136 offset:1024
	ds_read_b128 v[164:167], v136 offset:2048
	ds_read_b128 v[168:171], v136 offset:3072
	v_add_u32_e32 v136, s53, v150
	ds_read_b128 v[172:175], v136
	ds_read_b128 v[176:179], v136 offset:1024
	ds_read_b128 v[180:183], v136 offset:2048
	ds_read_b128 v[186:189], v136 offset:3072
	s_add_u32 s26, s26, 0x40000
	s_addc_u32 s27, s27, 0
	s_mov_b32 m0, s35
	v_lshl_add_u64 v[230:231], s[98:99], 0, v[130:131]
	s_add_i32 s100, s42, s30
	s_mov_b32 m0, s100
	s_nop 0
	global_load_lds_dwordx4 v[230:231], off
	v_lshl_add_u64 v[230:231], s[98:99], 0, v[134:135]
	s_add_i32 m0, s100, 0x2000
	s_nop 0
	global_load_lds_dwordx4 v[230:231], off
	s_mov_b32 m0, s35
	s_nop 0
	v_lshl_add_u64 v[230:231], s[26:27], 0, v[128:129]
	ds_read_b128 v[192:195], v154 offset:32768
	ds_read_b128 v[196:199], v154 offset:33792
	ds_read_b128 v[200:203], v154 offset:34816
	ds_read_b128 v[204:207], v154 offset:35840
	ds_read_b128 v[208:211], v154 offset:36864
	ds_read_b128 v[212:215], v154 offset:37888
	ds_read_b128 v[216:219], v154 offset:38912
	ds_read_b128 v[220:223], v154 offset:39936
	global_load_lds_dwordx4 v[230:231], off
	v_lshl_add_u64 v[230:231], s[26:27], 0, v[132:133]
	s_mov_b32 m0, s36
	s_nop 0
	global_load_lds_dwordx4 v[230:231], off
	s_waitcnt vmcnt(8)
	s_waitcnt lgkmcnt(0)
	s_barrier
	s_setprio 1
	s_waitcnt lgkmcnt(0)
	v_mfma_f32_16x16x32_bf16 v[124:127], v[156:159], v[192:195], v[124:127]
	v_mfma_f32_16x16x32_bf16 v[120:123], v[164:167], v[192:195], v[120:123]
	v_mfma_f32_16x16x32_bf16 v[112:115], v[156:159], v[200:203], v[112:115]
	v_mfma_f32_16x16x32_bf16 v[104:107], v[164:167], v[200:203], v[104:107]
	v_mfma_f32_16x16x32_bf16 v[96:99], v[156:159], v[208:211], v[96:99]
	v_mfma_f32_16x16x32_bf16 v[88:91], v[164:167], v[208:211], v[88:91]
	v_mfma_f32_16x16x32_bf16 v[80:83], v[156:159], v[216:219], v[80:83]
	v_mfma_f32_16x16x32_bf16 v[72:75], v[164:167], v[216:219], v[72:75]
	v_mfma_f32_16x16x32_bf16 v[124:127], v[160:163], v[196:199], v[124:127]
	v_mfma_f32_16x16x32_bf16 v[120:123], v[168:171], v[196:199], v[120:123]
	v_mfma_f32_16x16x32_bf16 v[112:115], v[160:163], v[204:207], v[112:115]
	v_mfma_f32_16x16x32_bf16 v[104:107], v[168:171], v[204:207], v[104:107]
	v_mfma_f32_16x16x32_bf16 v[96:99], v[160:163], v[212:215], v[96:99]
	v_mfma_f32_16x16x32_bf16 v[88:91], v[168:171], v[212:215], v[88:91]
	v_mfma_f32_16x16x32_bf16 v[80:83], v[160:163], v[220:223], v[80:83]
	v_mfma_f32_16x16x32_bf16 v[72:75], v[168:171], v[220:223], v[72:75]
	s_setprio 0
	s_setprio 1
	v_mfma_f32_16x16x32_bf16 v[116:119], v[172:175], v[192:195], v[116:119]
	v_mfma_f32_16x16x32_bf16 v[108:111], v[180:183], v[192:195], v[108:111]
	v_mfma_f32_16x16x32_bf16 v[100:103], v[172:175], v[200:203], v[100:103]
	v_mfma_f32_16x16x32_bf16 v[92:95], v[180:183], v[200:203], v[92:95]
	v_mfma_f32_16x16x32_bf16 v[84:87], v[172:175], v[208:211], v[84:87]
	v_mfma_f32_16x16x32_bf16 v[76:79], v[180:183], v[208:211], v[76:79]
	v_mfma_f32_16x16x32_bf16 v[68:71], v[172:175], v[216:219], v[68:71]
	v_mfma_f32_16x16x32_bf16 v[64:67], v[180:183], v[216:219], v[64:67]
	v_mfma_f32_16x16x32_bf16 v[116:119], v[176:179], v[196:199], v[116:119]
	v_mfma_f32_16x16x32_bf16 v[108:111], v[186:189], v[196:199], v[108:111]
	v_mfma_f32_16x16x32_bf16 v[100:103], v[176:179], v[204:207], v[100:103]
	v_mfma_f32_16x16x32_bf16 v[92:95], v[186:189], v[204:207], v[92:95]
	v_mfma_f32_16x16x32_bf16 v[84:87], v[176:179], v[212:215], v[84:87]
	v_mfma_f32_16x16x32_bf16 v[76:79], v[186:189], v[212:215], v[76:79]
	v_mfma_f32_16x16x32_bf16 v[68:71], v[176:179], v[220:223], v[68:71]
	v_mfma_f32_16x16x32_bf16 v[64:67], v[186:189], v[220:223], v[64:67]
	s_setprio 0
	s_barrier
	s_add_i32 s26, s52, s30
	v_lshl_add_u64 v[148:149], v[148:149], 0, s[6:7]
	s_mov_b32 m0, s26
	ds_read_b128 v[192:195], v154 offset:49152
	ds_read_b128 v[196:199], v154 offset:50176
	ds_read_b128 v[200:203], v154 offset:51200
	ds_read_b128 v[204:207], v154 offset:52224
	ds_read_b128 v[208:211], v154 offset:53248
	ds_read_b128 v[212:215], v154 offset:54272
	ds_read_b128 v[216:219], v154 offset:55296
	ds_read_b128 v[220:223], v154 offset:56320
	global_load_lds_dwordx4 v[148:149], off
	s_add_i32 m0, s26, 0x2000
	s_add_u32 s24, s24, 0x40080
	v_lshl_add_u64 v[148:149], v[224:225], 0, s[6:7]
	s_addc_u32 s25, s25, 0
	s_add_i32 s26, s53, s30
	global_load_lds_dwordx4 v[148:149], off
	v_lshl_add_u64 v[148:149], s[24:25], 0, v[130:131]
	s_mov_b32 m0, s26
	s_nop 0
	s_nop 0
	v_lshl_add_u64 v[148:149], s[24:25], 0, v[134:135]
	s_add_i32 m0, s26, 0x2000
	s_nop 0
	s_nop 0
	v_lshl_add_u64 v[148:149], v[226:227], 0, s[6:7]
	s_mov_b32 m0, s39
	s_nop 0
	global_load_lds_dwordx4 v[148:149], off
	v_lshl_add_u64 v[148:149], v[228:229], 0, s[6:7]
	s_mov_b32 m0, s40
	s_nop 0
	global_load_lds_dwordx4 v[148:149], off
	s_waitcnt vmcnt(6)
	s_waitcnt lgkmcnt(0)
	s_barrier
	s_setprio 1
	s_waitcnt lgkmcnt(0)
	v_mfma_f32_16x16x32_bf16 v[60:63], v[156:159], v[192:195], v[60:63]
	v_mfma_f32_16x16x32_bf16 v[56:59], v[164:167], v[192:195], v[56:59]
	v_mfma_f32_16x16x32_bf16 v[48:51], v[156:159], v[200:203], v[48:51]
	v_mfma_f32_16x16x32_bf16 v[40:43], v[164:167], v[200:203], v[40:43]
	v_mfma_f32_16x16x32_bf16 v[32:35], v[156:159], v[208:211], v[32:35]
	v_mfma_f32_16x16x32_bf16 v[24:27], v[164:167], v[208:211], v[24:27]
	v_mfma_f32_16x16x32_bf16 v[16:19], v[156:159], v[216:219], v[16:19]
	v_mfma_f32_16x16x32_bf16 v[8:11], v[164:167], v[216:219], v[8:11]
	v_mfma_f32_16x16x32_bf16 v[60:63], v[160:163], v[196:199], v[60:63]
	v_mfma_f32_16x16x32_bf16 v[56:59], v[168:171], v[196:199], v[56:59]
	v_mfma_f32_16x16x32_bf16 v[48:51], v[160:163], v[204:207], v[48:51]
	v_mfma_f32_16x16x32_bf16 v[40:43], v[168:171], v[204:207], v[40:43]
	v_mfma_f32_16x16x32_bf16 v[32:35], v[160:163], v[212:215], v[32:35]
	v_mfma_f32_16x16x32_bf16 v[24:27], v[168:171], v[212:215], v[24:27]
	v_mfma_f32_16x16x32_bf16 v[16:19], v[160:163], v[220:223], v[16:19]
	v_mfma_f32_16x16x32_bf16 v[8:11], v[168:171], v[220:223], v[8:11]
	s_setprio 0
	s_setprio 1
	v_mfma_f32_16x16x32_bf16 v[52:55], v[172:175], v[192:195], v[52:55]
	v_mfma_f32_16x16x32_bf16 v[44:47], v[180:183], v[192:195], v[44:47]
	v_mfma_f32_16x16x32_bf16 v[36:39], v[172:175], v[200:203], v[36:39]
	v_mfma_f32_16x16x32_bf16 v[28:31], v[180:183], v[200:203], v[28:31]
	v_mfma_f32_16x16x32_bf16 v[20:23], v[172:175], v[208:211], v[20:23]
	v_mfma_f32_16x16x32_bf16 v[12:15], v[180:183], v[208:211], v[12:15]
	v_mfma_f32_16x16x32_bf16 v[4:7], v[172:175], v[216:219], v[4:7]
	v_mfma_f32_16x16x32_bf16 v[0:3], v[180:183], v[216:219], v[0:3]
	v_mfma_f32_16x16x32_bf16 v[52:55], v[176:179], v[196:199], v[52:55]
	v_mfma_f32_16x16x32_bf16 v[44:47], v[186:189], v[196:199], v[44:47]
	v_mfma_f32_16x16x32_bf16 v[36:39], v[176:179], v[204:207], v[36:39]
	v_mfma_f32_16x16x32_bf16 v[28:31], v[186:189], v[204:207], v[28:31]
	v_mfma_f32_16x16x32_bf16 v[20:23], v[176:179], v[212:215], v[20:23]
	v_mfma_f32_16x16x32_bf16 v[12:15], v[186:189], v[212:215], v[12:15]
	v_mfma_f32_16x16x32_bf16 v[4:7], v[176:179], v[220:223], v[4:7]
	v_mfma_f32_16x16x32_bf16 v[0:3], v[186:189], v[220:223], v[0:3]
	s_setprio 0
	s_barrier
	s_add_i32 s51, s51, 2
	s_add_u32 s22, s22, 0x100
	s_addc_u32 s23, s23, 0
	s_add_u32 s49, s49, 0x100
	s_addc_u32 s50, s50, 0
	s_cmp_gt_u32 s51, 13
	s_cbranch_scc0 .LBB0_226
	s_and_b64 vcc, exec, s[8:9]
	s_cbranch_vccz .LBB0_229
	s_barrier

.LBB0_380:
	s_add_u32 s98, s51, 0x3ff80
	s_addc_u32 s99, s52, 0
	ds_read_b128 v[76:79], v188
	ds_read_b128 v[84:87], v188 offset:1024
	ds_read_b128 v[88:91], v188 offset:2048
	ds_read_b128 v[96:99], v188 offset:3072
	ds_read_b128 v[144:147], v189
	ds_read_b128 v[148:151], v189 offset:1024
	ds_read_b128 v[152:155], v189 offset:2048
	ds_read_b128 v[156:159], v189 offset:3072
	s_add_u32 s28, s26, 0xfffc0080
	s_addc_u32 s29, s27, -1
	s_cmp_eq_u32 s53, 12
	s_cselect_b32 s31, s17, s29
	s_cselect_b32 s30, s23, s28
	s_cselect_b32 s29, s15, s52
	s_cselect_b32 s28, s50, s51
	v_lshl_add_u64 v[214:215], s[98:99], 0, v[160:161]
	s_add_i32 m0, s35, 0x1c000
	s_nop 0
	global_load_lds_dwordx4 v[214:215], off
	v_lshl_add_u64 v[214:215], s[98:99], 0, v[162:163]
	s_add_i32 m0, s35, 0x1e000
	s_nop 0
	global_load_lds_dwordx4 v[214:215], off
	v_lshl_add_u64 v[214:215], s[26:27], 0, v[164:165]
	s_add_i32 m0, s25, 0xc000
	ds_read_b128 v[172:175], v191
	ds_read_b128 v[176:179], v191 offset:1024
	ds_read_b128 v[180:183], v191 offset:2048
	ds_read_b128 v[194:197], v191 offset:3072
	ds_read_b128 v[198:201], v191 offset:4096
	ds_read_b128 v[202:205], v191 offset:5120
	ds_read_b128 v[206:209], v191 offset:6144
	ds_read_b128 v[210:213], v191 offset:7168
	global_load_lds_dwordx4 v[214:215], off
	v_lshl_add_u64 v[214:215], s[26:27], 0, v[166:167]
	s_add_i32 m0, s25, 0xe000
	s_nop 0
	global_load_lds_dwordx4 v[214:215], off
	s_waitcnt vmcnt(8)
	s_waitcnt lgkmcnt(0)
	s_barrier
	s_setprio 1
	s_waitcnt lgkmcnt(0)
	v_mfma_f32_16x16x32_bf16 v[140:143], v[76:79], v[172:175], v[140:143]
	v_mfma_f32_16x16x32_bf16 v[136:139], v[88:91], v[172:175], v[136:139]
	v_mfma_f32_16x16x32_bf16 v[124:127], v[76:79], v[180:183], v[124:127]
	v_mfma_f32_16x16x32_bf16 v[120:123], v[88:91], v[180:183], v[120:123]
	v_mfma_f32_16x16x32_bf16 v[108:111], v[76:79], v[198:201], v[108:111]
	v_mfma_f32_16x16x32_bf16 v[104:107], v[88:91], v[198:201], v[104:107]
	v_mfma_f32_16x16x32_bf16 v[80:83], v[76:79], v[206:209], v[80:83]
	v_mfma_f32_16x16x32_bf16 v[72:75], v[88:91], v[206:209], v[72:75]
	v_mfma_f32_16x16x32_bf16 v[140:143], v[84:87], v[176:179], v[140:143]
	v_mfma_f32_16x16x32_bf16 v[136:139], v[96:99], v[176:179], v[136:139]
	v_mfma_f32_16x16x32_bf16 v[124:127], v[84:87], v[194:197], v[124:127]
	v_mfma_f32_16x16x32_bf16 v[120:123], v[96:99], v[194:197], v[120:123]
	v_mfma_f32_16x16x32_bf16 v[108:111], v[84:87], v[202:205], v[108:111]
	v_mfma_f32_16x16x32_bf16 v[104:107], v[96:99], v[202:205], v[104:107]
	v_mfma_f32_16x16x32_bf16 v[80:83], v[84:87], v[210:213], v[80:83]
	v_mfma_f32_16x16x32_bf16 v[72:75], v[96:99], v[210:213], v[72:75]
	s_setprio 0
	s_setprio 1
	v_mfma_f32_16x16x32_bf16 v[132:135], v[144:147], v[172:175], v[132:135]
	v_mfma_f32_16x16x32_bf16 v[128:131], v[152:155], v[172:175], v[128:131]
	v_mfma_f32_16x16x32_bf16 v[116:119], v[144:147], v[180:183], v[116:119]
	v_mfma_f32_16x16x32_bf16 v[112:115], v[152:155], v[180:183], v[112:115]
	v_mfma_f32_16x16x32_bf16 v[100:103], v[144:147], v[198:201], v[100:103]
	v_mfma_f32_16x16x32_bf16 v[92:95], v[152:155], v[198:201], v[92:95]
	v_mfma_f32_16x16x32_bf16 v[68:71], v[144:147], v[206:209], v[68:71]
	v_mfma_f32_16x16x32_bf16 v[64:67], v[152:155], v[206:209], v[64:67]
	v_mfma_f32_16x16x32_bf16 v[132:135], v[148:151], v[176:179], v[132:135]
	v_mfma_f32_16x16x32_bf16 v[128:131], v[156:159], v[176:179], v[128:131]
	v_mfma_f32_16x16x32_bf16 v[116:119], v[148:151], v[194:197], v[116:119]
	v_mfma_f32_16x16x32_bf16 v[112:115], v[156:159], v[194:197], v[112:115]
	v_mfma_f32_16x16x32_bf16 v[100:103], v[148:151], v[202:205], v[100:103]
	v_mfma_f32_16x16x32_bf16 v[92:95], v[156:159], v[202:205], v[92:95]
	v_mfma_f32_16x16x32_bf16 v[68:71], v[148:151], v[210:213], v[68:71]
	v_mfma_f32_16x16x32_bf16 v[64:67], v[156:159], v[210:213], v[64:67]
	s_setprio 0
	s_barrier
	s_add_i32 s54, s48, s35
	v_lshl_add_u64 v[214:215], s[28:29], 0, v[160:161]
	s_mov_b32 m0, s54
	ds_read_b128 v[172:175], v191 offset:16384
	ds_read_b128 v[176:179], v191 offset:17408
	ds_read_b128 v[180:183], v191 offset:18432
	ds_read_b128 v[194:197], v191 offset:19456
	ds_read_b128 v[198:201], v191 offset:20480
	ds_read_b128 v[202:205], v191 offset:21504
	ds_read_b128 v[206:209], v191 offset:22528
	ds_read_b128 v[210:213], v191 offset:23552
	global_load_lds_dwordx4 v[214:215], off
	s_add_i32 m0, s54, 0x2000
	s_add_u32 s54, s28, 0x40000
	v_lshl_add_u64 v[216:217], s[28:29], 0, v[162:163]
	s_addc_u32 s55, s29, 0
	s_add_i32 s56, s49, s35
	global_load_lds_dwordx4 v[216:217], off
	v_lshl_add_u64 v[218:219], s[54:55], 0, v[160:161]
	s_mov_b32 m0, s56
	v_lshl_add_u64 v[220:221], s[30:31], 0, v[162:163]
	s_nop 0
	v_lshl_add_u64 v[218:219], s[54:55], 0, v[162:163]
	s_add_i32 m0, s56, 0x2000
	s_nop 0
	s_nop 0
	v_lshl_add_u64 v[218:219], s[30:31], 0, v[160:161]
	s_mov_b32 m0, s25
	s_nop 0
	global_load_lds_dwordx4 v[218:219], off
	s_mov_b32 m0, s36
	s_nop 0
	global_load_lds_dwordx4 v[220:221], off
	s_waitcnt vmcnt(6)
	s_waitcnt lgkmcnt(0)
	s_barrier
	s_setprio 1
	s_waitcnt lgkmcnt(0)
	v_mfma_f32_16x16x32_bf16 v[60:63], v[76:79], v[172:175], v[60:63]
	v_mfma_f32_16x16x32_bf16 v[56:59], v[88:91], v[172:175], v[56:59]
	v_mfma_f32_16x16x32_bf16 v[44:47], v[76:79], v[180:183], v[44:47]
	v_mfma_f32_16x16x32_bf16 v[40:43], v[88:91], v[180:183], v[40:43]
	v_mfma_f32_16x16x32_bf16 v[28:31], v[76:79], v[198:201], v[28:31]
	v_mfma_f32_16x16x32_bf16 v[24:27], v[88:91], v[198:201], v[24:27]
	v_mfma_f32_16x16x32_bf16 v[12:15], v[76:79], v[206:209], v[12:15]
	v_mfma_f32_16x16x32_bf16 v[8:11], v[88:91], v[206:209], v[8:11]
	v_mfma_f32_16x16x32_bf16 v[60:63], v[84:87], v[176:179], v[60:63]
	v_mfma_f32_16x16x32_bf16 v[56:59], v[96:99], v[176:179], v[56:59]
	v_mfma_f32_16x16x32_bf16 v[44:47], v[84:87], v[194:197], v[44:47]
	v_mfma_f32_16x16x32_bf16 v[40:43], v[96:99], v[194:197], v[40:43]
	v_mfma_f32_16x16x32_bf16 v[28:31], v[84:87], v[202:205], v[28:31]
	v_mfma_f32_16x16x32_bf16 v[24:27], v[96:99], v[202:205], v[24:27]
	v_mfma_f32_16x16x32_bf16 v[12:15], v[84:87], v[210:213], v[12:15]
	v_mfma_f32_16x16x32_bf16 v[8:11], v[96:99], v[210:213], v[8:11]
	s_setprio 0
	s_setprio 1
	v_mfma_f32_16x16x32_bf16 v[52:55], v[144:147], v[172:175], v[52:55]
	v_mfma_f32_16x16x32_bf16 v[48:51], v[152:155], v[172:175], v[48:51]
	v_mfma_f32_16x16x32_bf16 v[36:39], v[144:147], v[180:183], v[36:39]
	v_mfma_f32_16x16x32_bf16 v[32:35], v[152:155], v[180:183], v[32:35]
	v_mfma_f32_16x16x32_bf16 v[20:23], v[144:147], v[198:201], v[20:23]
	v_mfma_f32_16x16x32_bf16 v[16:19], v[152:155], v[198:201], v[16:19]
	v_mfma_f32_16x16x32_bf16 v[4:7], v[144:147], v[206:209], v[4:7]
	v_mfma_f32_16x16x32_bf16 v[0:3], v[152:155], v[206:209], v[0:3]
	v_mfma_f32_16x16x32_bf16 v[52:55], v[148:151], v[176:179], v[52:55]
	v_mfma_f32_16x16x32_bf16 v[48:51], v[156:159], v[176:179], v[48:51]
	v_mfma_f32_16x16x32_bf16 v[36:39], v[148:151], v[194:197], v[36:39]
	v_mfma_f32_16x16x32_bf16 v[32:35], v[156:159], v[194:197], v[32:35]
	v_mfma_f32_16x16x32_bf16 v[20:23], v[148:151], v[202:205], v[20:23]
	v_mfma_f32_16x16x32_bf16 v[16:19], v[156:159], v[202:205], v[16:19]
	v_mfma_f32_16x16x32_bf16 v[4:7], v[148:151], v[210:213], v[4:7]
	v_mfma_f32_16x16x32_bf16 v[0:3], v[156:159], v[210:213], v[0:3]
	s_setprio 0
	s_barrier
	s_add_u32 s98, s28, 0x40000
	s_addc_u32 s99, s29, 0
	s_add_i32 s54, 0, 0x18000
	s_add_i32 s55, 0, 0x1c000
	v_add_u32_e32 v96, s54, v186
	v_add_u32_e32 v156, s55, v186
	ds_read_b128 v[76:79], v96
	ds_read_b128 v[84:87], v96 offset:1024
	ds_read_b128 v[88:91], v96 offset:2048
	ds_read_b128 v[96:99], v96 offset:3072
	ds_read_b128 v[144:147], v156
	ds_read_b128 v[148:151], v156 offset:1024
	ds_read_b128 v[152:155], v156 offset:2048
	ds_read_b128 v[156:159], v156 offset:3072
	s_add_u32 s30, s30, 0x40000
	s_addc_u32 s31, s31, 0
	s_mov_b32 m0, s37
	v_lshl_add_u64 v[222:223], s[98:99], 0, v[160:161]
	s_add_i32 s100, s49, s35
	s_mov_b32 m0, s100
	s_nop 0
	global_load_lds_dwordx4 v[222:223], off
	v_lshl_add_u64 v[222:223], s[98:99], 0, v[162:163]
	s_add_i32 m0, s100, 0x2000
	s_nop 0
	global_load_lds_dwordx4 v[222:223], off
	s_mov_b32 m0, s37
	s_nop 0
	v_lshl_add_u64 v[222:223], s[30:31], 0, v[160:161]
	ds_read_b128 v[172:175], v191 offset:32768
	ds_read_b128 v[176:179], v191 offset:33792
	ds_read_b128 v[180:183], v191 offset:34816
	ds_read_b128 v[194:197], v191 offset:35840
	ds_read_b128 v[198:201], v191 offset:36864
	ds_read_b128 v[202:205], v191 offset:37888
	ds_read_b128 v[206:209], v191 offset:38912
	ds_read_b128 v[210:213], v191 offset:39936
	global_load_lds_dwordx4 v[222:223], off
	v_lshl_add_u64 v[222:223], s[30:31], 0, v[162:163]
	s_mov_b32 m0, s38
	s_nop 0
	global_load_lds_dwordx4 v[222:223], off
	s_waitcnt vmcnt(8)
	s_waitcnt lgkmcnt(0)
	s_barrier
	s_setprio 1
	s_waitcnt lgkmcnt(0)
	v_mfma_f32_16x16x32_bf16 v[140:143], v[76:79], v[172:175], v[140:143]
	v_mfma_f32_16x16x32_bf16 v[136:139], v[88:91], v[172:175], v[136:139]
	v_mfma_f32_16x16x32_bf16 v[124:127], v[76:79], v[180:183], v[124:127]
	v_mfma_f32_16x16x32_bf16 v[120:123], v[88:91], v[180:183], v[120:123]
	v_mfma_f32_16x16x32_bf16 v[108:111], v[76:79], v[198:201], v[108:111]
	v_mfma_f32_16x16x32_bf16 v[104:107], v[88:91], v[198:201], v[104:107]
	v_mfma_f32_16x16x32_bf16 v[80:83], v[76:79], v[206:209], v[80:83]
	v_mfma_f32_16x16x32_bf16 v[72:75], v[88:91], v[206:209], v[72:75]
	v_mfma_f32_16x16x32_bf16 v[140:143], v[84:87], v[176:179], v[140:143]
	v_mfma_f32_16x16x32_bf16 v[136:139], v[96:99], v[176:179], v[136:139]
	v_mfma_f32_16x16x32_bf16 v[124:127], v[84:87], v[194:197], v[124:127]
	v_mfma_f32_16x16x32_bf16 v[120:123], v[96:99], v[194:197], v[120:123]
	v_mfma_f32_16x16x32_bf16 v[108:111], v[84:87], v[202:205], v[108:111]
	v_mfma_f32_16x16x32_bf16 v[104:107], v[96:99], v[202:205], v[104:107]
	v_mfma_f32_16x16x32_bf16 v[80:83], v[84:87], v[210:213], v[80:83]
	v_mfma_f32_16x16x32_bf16 v[72:75], v[96:99], v[210:213], v[72:75]
	s_setprio 0
	s_setprio 1
	v_mfma_f32_16x16x32_bf16 v[132:135], v[144:147], v[172:175], v[132:135]
	v_mfma_f32_16x16x32_bf16 v[128:131], v[152:155], v[172:175], v[128:131]
	v_mfma_f32_16x16x32_bf16 v[116:119], v[144:147], v[180:183], v[116:119]
	v_mfma_f32_16x16x32_bf16 v[112:115], v[152:155], v[180:183], v[112:115]
	v_mfma_f32_16x16x32_bf16 v[100:103], v[144:147], v[198:201], v[100:103]
	v_mfma_f32_16x16x32_bf16 v[92:95], v[152:155], v[198:201], v[92:95]
	v_mfma_f32_16x16x32_bf16 v[68:71], v[144:147], v[206:209], v[68:71]
	v_mfma_f32_16x16x32_bf16 v[64:67], v[152:155], v[206:209], v[64:67]
	v_mfma_f32_16x16x32_bf16 v[132:135], v[148:151], v[176:179], v[132:135]
	v_mfma_f32_16x16x32_bf16 v[128:131], v[156:159], v[176:179], v[128:131]
	v_mfma_f32_16x16x32_bf16 v[116:119], v[148:151], v[194:197], v[116:119]
	v_mfma_f32_16x16x32_bf16 v[112:115], v[156:159], v[194:197], v[112:115]
	v_mfma_f32_16x16x32_bf16 v[100:103], v[148:151], v[202:205], v[100:103]
	v_mfma_f32_16x16x32_bf16 v[92:95], v[156:159], v[202:205], v[92:95]
	v_mfma_f32_16x16x32_bf16 v[68:71], v[148:151], v[210:213], v[68:71]
	v_mfma_f32_16x16x32_bf16 v[64:67], v[156:159], v[210:213], v[64:67]
	s_setprio 0
	s_barrier
	s_add_i32 s30, s54, s35
	v_lshl_add_u64 v[214:215], v[214:215], 0, s[10:11]
	s_mov_b32 m0, s30
	ds_read_b128 v[172:175], v191 offset:49152
	ds_read_b128 v[176:179], v191 offset:50176
	ds_read_b128 v[180:183], v191 offset:51200
	ds_read_b128 v[194:197], v191 offset:52224
	ds_read_b128 v[198:201], v191 offset:53248
	ds_read_b128 v[202:205], v191 offset:54272
	ds_read_b128 v[206:209], v191 offset:55296
	ds_read_b128 v[210:213], v191 offset:56320
	global_load_lds_dwordx4 v[214:215], off
	s_add_i32 m0, s30, 0x2000
	s_add_u32 s28, s28, 0x40080
	v_lshl_add_u64 v[214:215], v[216:217], 0, s[10:11]
	s_addc_u32 s29, s29, 0
	s_add_i32 s30, s55, s35
	global_load_lds_dwordx4 v[214:215], off
	v_lshl_add_u64 v[214:215], s[28:29], 0, v[160:161]
	s_mov_b32 m0, s30
	s_nop 0
	s_nop 0
	v_lshl_add_u64 v[214:215], s[28:29], 0, v[162:163]
	s_add_i32 m0, s30, 0x2000
	s_nop 0
	s_nop 0
	v_lshl_add_u64 v[214:215], v[218:219], 0, s[10:11]
	s_mov_b32 m0, s46
	s_nop 0
	global_load_lds_dwordx4 v[214:215], off
	v_lshl_add_u64 v[214:215], v[220:221], 0, s[10:11]
	s_mov_b32 m0, s47
	s_nop 0
	global_load_lds_dwordx4 v[214:215], off
	s_waitcnt vmcnt(6)
	s_waitcnt lgkmcnt(0)
	s_barrier
	s_setprio 1
	s_waitcnt lgkmcnt(0)
	v_mfma_f32_16x16x32_bf16 v[60:63], v[76:79], v[172:175], v[60:63]
	v_mfma_f32_16x16x32_bf16 v[56:59], v[88:91], v[172:175], v[56:59]
	v_mfma_f32_16x16x32_bf16 v[44:47], v[76:79], v[180:183], v[44:47]
	v_mfma_f32_16x16x32_bf16 v[40:43], v[88:91], v[180:183], v[40:43]
	v_mfma_f32_16x16x32_bf16 v[28:31], v[76:79], v[198:201], v[28:31]
	v_mfma_f32_16x16x32_bf16 v[24:27], v[88:91], v[198:201], v[24:27]
	v_mfma_f32_16x16x32_bf16 v[12:15], v[76:79], v[206:209], v[12:15]
	v_mfma_f32_16x16x32_bf16 v[8:11], v[88:91], v[206:209], v[8:11]
	v_mfma_f32_16x16x32_bf16 v[60:63], v[84:87], v[176:179], v[60:63]
	v_mfma_f32_16x16x32_bf16 v[56:59], v[96:99], v[176:179], v[56:59]
	v_mfma_f32_16x16x32_bf16 v[44:47], v[84:87], v[194:197], v[44:47]
	v_mfma_f32_16x16x32_bf16 v[40:43], v[96:99], v[194:197], v[40:43]
	v_mfma_f32_16x16x32_bf16 v[28:31], v[84:87], v[202:205], v[28:31]
	v_mfma_f32_16x16x32_bf16 v[24:27], v[96:99], v[202:205], v[24:27]
	v_mfma_f32_16x16x32_bf16 v[12:15], v[84:87], v[210:213], v[12:15]
	v_mfma_f32_16x16x32_bf16 v[8:11], v[96:99], v[210:213], v[8:11]
	s_setprio 0
	s_setprio 1
	v_mfma_f32_16x16x32_bf16 v[52:55], v[144:147], v[172:175], v[52:55]
	v_mfma_f32_16x16x32_bf16 v[48:51], v[152:155], v[172:175], v[48:51]
	v_mfma_f32_16x16x32_bf16 v[36:39], v[144:147], v[180:183], v[36:39]
	v_mfma_f32_16x16x32_bf16 v[32:35], v[152:155], v[180:183], v[32:35]
	v_mfma_f32_16x16x32_bf16 v[20:23], v[144:147], v[198:201], v[20:23]
	v_mfma_f32_16x16x32_bf16 v[16:19], v[152:155], v[198:201], v[16:19]
	v_mfma_f32_16x16x32_bf16 v[4:7], v[144:147], v[206:209], v[4:7]
	v_mfma_f32_16x16x32_bf16 v[0:3], v[152:155], v[206:209], v[0:3]
	v_mfma_f32_16x16x32_bf16 v[52:55], v[148:151], v[176:179], v[52:55]
	v_mfma_f32_16x16x32_bf16 v[48:51], v[156:159], v[176:179], v[48:51]
	v_mfma_f32_16x16x32_bf16 v[36:39], v[148:151], v[194:197], v[36:39]
	v_mfma_f32_16x16x32_bf16 v[32:35], v[156:159], v[194:197], v[32:35]
	v_mfma_f32_16x16x32_bf16 v[20:23], v[148:151], v[202:205], v[20:23]
	v_mfma_f32_16x16x32_bf16 v[16:19], v[156:159], v[202:205], v[16:19]
	v_mfma_f32_16x16x32_bf16 v[4:7], v[148:151], v[210:213], v[4:7]
	v_mfma_f32_16x16x32_bf16 v[0:3], v[156:159], v[210:213], v[0:3]
	s_setprio 0
	s_barrier
	s_add_i32 s53, s53, 2
	s_add_u32 s26, s26, 0x100
	s_addc_u32 s27, s27, 0
	s_add_u32 s51, s51, 0x100
	s_addc_u32 s52, s52, 0
	s_cmp_gt_u32 s53, 13
	s_cbranch_scc0 .LBB0_380
	s_and_b64 vcc, exec, s[12:13]
	s_cbranch_vccz .LBB0_383
	s_barrier

.LBB0_588:
	s_add_u32 s98, s41, 0xaff80
	s_addc_u32 s99, s42, 0
	ds_read_b128 v[128:131], v179
	ds_read_b128 v[132:135], v179 offset:1024
	ds_read_b128 v[136:139], v179 offset:2048
	ds_read_b128 v[140:143], v179 offset:3072
	ds_read_b128 v[144:147], v180
	ds_read_b128 v[148:151], v180 offset:1024
	ds_read_b128 v[164:167], v180 offset:2048
	ds_read_b128 v[168:171], v180 offset:3072
	s_add_u32 s16, s14, 0xfff50080
	s_addc_u32 s17, s15, -1
	s_cmp_eq_u32 s43, 40
	s_cselect_b32 s19, s1, s17
	s_cselect_b32 s18, s0, s16
	s_cselect_b32 s17, s13, s42
	s_cselect_b32 s16, s12, s41
	v_lshl_add_u64 v[172:173], s[98:99], 0, v[152:153]
	s_add_i32 m0, s22, 0x1c000
	s_nop 0
	global_load_lds_dwordx4 v[172:173], off
	v_lshl_add_u64 v[172:173], s[98:99], 0, v[154:155]
	s_add_i32 m0, s22, 0x1e000
	s_nop 0
	global_load_lds_dwordx4 v[172:173], off
	v_lshl_add_u64 v[172:173], s[14:15], 0, v[156:157]
	s_add_i32 m0, s24, 0xc000
	ds_read_b128 v[186:189], v181
	ds_read_b128 v[192:195], v181 offset:1024
	ds_read_b128 v[196:199], v181 offset:2048
	ds_read_b128 v[200:203], v181 offset:3072
	ds_read_b128 v[204:207], v181 offset:4096
	ds_read_b128 v[208:211], v181 offset:5120
	ds_read_b128 v[212:215], v181 offset:6144
	ds_read_b128 v[216:219], v181 offset:7168
	global_load_lds_dwordx4 v[172:173], off
	v_lshl_add_u64 v[172:173], s[14:15], 0, v[158:159]
	s_add_i32 m0, s24, 0xe000
	s_nop 0
	global_load_lds_dwordx4 v[172:173], off
	s_waitcnt vmcnt(8)
	s_waitcnt lgkmcnt(0)
	s_barrier
	s_setprio 1
	s_waitcnt lgkmcnt(0)
	v_mfma_f32_16x16x32_bf16 v[124:127], v[128:131], v[186:189], v[124:127]
	v_mfma_f32_16x16x32_bf16 v[120:123], v[136:139], v[186:189], v[120:123]
	v_mfma_f32_16x16x32_bf16 v[116:119], v[128:131], v[196:199], v[116:119]
	v_mfma_f32_16x16x32_bf16 v[112:115], v[136:139], v[196:199], v[112:115]
	v_mfma_f32_16x16x32_bf16 v[100:103], v[128:131], v[204:207], v[100:103]
	v_mfma_f32_16x16x32_bf16 v[88:91], v[136:139], v[204:207], v[88:91]
	v_mfma_f32_16x16x32_bf16 v[84:87], v[128:131], v[212:215], v[84:87]
	v_mfma_f32_16x16x32_bf16 v[76:79], v[136:139], v[212:215], v[76:79]
	v_mfma_f32_16x16x32_bf16 v[124:127], v[132:135], v[192:195], v[124:127]
	v_mfma_f32_16x16x32_bf16 v[120:123], v[140:143], v[192:195], v[120:123]
	v_mfma_f32_16x16x32_bf16 v[116:119], v[132:135], v[200:203], v[116:119]
	v_mfma_f32_16x16x32_bf16 v[112:115], v[140:143], v[200:203], v[112:115]
	v_mfma_f32_16x16x32_bf16 v[100:103], v[132:135], v[208:211], v[100:103]
	v_mfma_f32_16x16x32_bf16 v[88:91], v[140:143], v[208:211], v[88:91]
	v_mfma_f32_16x16x32_bf16 v[84:87], v[132:135], v[216:219], v[84:87]
	v_mfma_f32_16x16x32_bf16 v[76:79], v[140:143], v[216:219], v[76:79]
	s_setprio 0
	s_setprio 1
	v_mfma_f32_16x16x32_bf16 v[108:111], v[144:147], v[186:189], v[108:111]
	v_mfma_f32_16x16x32_bf16 v[104:107], v[164:167], v[186:189], v[104:107]
	v_mfma_f32_16x16x32_bf16 v[96:99], v[144:147], v[196:199], v[96:99]
	v_mfma_f32_16x16x32_bf16 v[92:95], v[164:167], v[196:199], v[92:95]
	v_mfma_f32_16x16x32_bf16 v[80:83], v[144:147], v[204:207], v[80:83]
	v_mfma_f32_16x16x32_bf16 v[72:75], v[164:167], v[204:207], v[72:75]
	v_mfma_f32_16x16x32_bf16 v[68:71], v[144:147], v[212:215], v[68:71]
	v_mfma_f32_16x16x32_bf16 v[64:67], v[164:167], v[212:215], v[64:67]
	v_mfma_f32_16x16x32_bf16 v[108:111], v[148:151], v[192:195], v[108:111]
	v_mfma_f32_16x16x32_bf16 v[104:107], v[168:171], v[192:195], v[104:107]
	v_mfma_f32_16x16x32_bf16 v[96:99], v[148:151], v[200:203], v[96:99]
	v_mfma_f32_16x16x32_bf16 v[92:95], v[168:171], v[200:203], v[92:95]
	v_mfma_f32_16x16x32_bf16 v[80:83], v[148:151], v[208:211], v[80:83]
	v_mfma_f32_16x16x32_bf16 v[72:75], v[168:171], v[208:211], v[72:75]
	v_mfma_f32_16x16x32_bf16 v[68:71], v[148:151], v[216:219], v[68:71]
	v_mfma_f32_16x16x32_bf16 v[64:67], v[168:171], v[216:219], v[64:67]
	s_setprio 0
	s_barrier
	s_add_i32 s44, s35, s22
	v_lshl_add_u64 v[172:173], s[16:17], 0, v[152:153]
	s_mov_b32 m0, s44
	ds_read_b128 v[186:189], v181 offset:16384
	ds_read_b128 v[192:195], v181 offset:17408
	ds_read_b128 v[196:199], v181 offset:18432
	ds_read_b128 v[200:203], v181 offset:19456
	ds_read_b128 v[204:207], v181 offset:20480
	ds_read_b128 v[208:211], v181 offset:21504
	ds_read_b128 v[212:215], v181 offset:22528
	ds_read_b128 v[216:219], v181 offset:23552
	global_load_lds_dwordx4 v[172:173], off
	s_add_i32 m0, s44, 0x2000
	s_add_u32 s44, s16, 0xb0000
	v_lshl_add_u64 v[182:183], s[16:17], 0, v[154:155]
	s_addc_u32 s45, s17, 0
	s_add_i32 s46, s36, s22
	global_load_lds_dwordx4 v[182:183], off
	v_lshl_add_u64 v[220:221], s[44:45], 0, v[152:153]
	s_mov_b32 m0, s46
	v_lshl_add_u64 v[222:223], s[18:19], 0, v[154:155]
	s_nop 0
	v_lshl_add_u64 v[220:221], s[44:45], 0, v[154:155]
	s_add_i32 m0, s46, 0x2000
	s_nop 0
	s_nop 0
	v_lshl_add_u64 v[220:221], s[18:19], 0, v[152:153]
	s_mov_b32 m0, s24
	s_nop 0
	global_load_lds_dwordx4 v[220:221], off
	s_mov_b32 m0, s25
	s_nop 0
	global_load_lds_dwordx4 v[222:223], off
	s_waitcnt vmcnt(6)
	s_waitcnt lgkmcnt(0)
	s_barrier
	s_setprio 1
	s_waitcnt lgkmcnt(0)
	v_mfma_f32_16x16x32_bf16 v[60:63], v[128:131], v[186:189], v[60:63]
	v_mfma_f32_16x16x32_bf16 v[56:59], v[136:139], v[186:189], v[56:59]
	v_mfma_f32_16x16x32_bf16 v[52:55], v[128:131], v[196:199], v[52:55]
	v_mfma_f32_16x16x32_bf16 v[48:51], v[136:139], v[196:199], v[48:51]
	v_mfma_f32_16x16x32_bf16 v[40:43], v[128:131], v[204:207], v[40:43]
	v_mfma_f32_16x16x32_bf16 v[28:31], v[136:139], v[204:207], v[28:31]
	v_mfma_f32_16x16x32_bf16 v[16:19], v[128:131], v[212:215], v[16:19]
	v_mfma_f32_16x16x32_bf16 v[8:11], v[136:139], v[212:215], v[8:11]
	v_mfma_f32_16x16x32_bf16 v[60:63], v[132:135], v[192:195], v[60:63]
	v_mfma_f32_16x16x32_bf16 v[56:59], v[140:143], v[192:195], v[56:59]
	v_mfma_f32_16x16x32_bf16 v[52:55], v[132:135], v[200:203], v[52:55]
	v_mfma_f32_16x16x32_bf16 v[48:51], v[140:143], v[200:203], v[48:51]
	v_mfma_f32_16x16x32_bf16 v[40:43], v[132:135], v[208:211], v[40:43]
	v_mfma_f32_16x16x32_bf16 v[28:31], v[140:143], v[208:211], v[28:31]
	v_mfma_f32_16x16x32_bf16 v[16:19], v[132:135], v[216:219], v[16:19]
	v_mfma_f32_16x16x32_bf16 v[8:11], v[140:143], v[216:219], v[8:11]
	s_setprio 0
	s_setprio 1
	v_mfma_f32_16x16x32_bf16 v[44:47], v[144:147], v[186:189], v[44:47]
	v_mfma_f32_16x16x32_bf16 v[36:39], v[164:167], v[186:189], v[36:39]
	v_mfma_f32_16x16x32_bf16 v[32:35], v[144:147], v[196:199], v[32:35]
	v_mfma_f32_16x16x32_bf16 v[24:27], v[164:167], v[196:199], v[24:27]
	v_mfma_f32_16x16x32_bf16 v[20:23], v[144:147], v[204:207], v[20:23]
	v_mfma_f32_16x16x32_bf16 v[12:15], v[164:167], v[204:207], v[12:15]
	v_mfma_f32_16x16x32_bf16 v[4:7], v[144:147], v[212:215], v[4:7]
	v_mfma_f32_16x16x32_bf16 v[0:3], v[164:167], v[212:215], v[0:3]
	v_mfma_f32_16x16x32_bf16 v[44:47], v[148:151], v[192:195], v[44:47]
	v_mfma_f32_16x16x32_bf16 v[36:39], v[168:171], v[192:195], v[36:39]
	v_mfma_f32_16x16x32_bf16 v[32:35], v[148:151], v[200:203], v[32:35]
	v_mfma_f32_16x16x32_bf16 v[24:27], v[168:171], v[200:203], v[24:27]
	v_mfma_f32_16x16x32_bf16 v[20:23], v[148:151], v[208:211], v[20:23]
	v_mfma_f32_16x16x32_bf16 v[12:15], v[168:171], v[208:211], v[12:15]
	v_mfma_f32_16x16x32_bf16 v[4:7], v[148:151], v[216:219], v[4:7]
	v_mfma_f32_16x16x32_bf16 v[0:3], v[168:171], v[216:219], v[0:3]
	s_setprio 0
	s_barrier
	s_add_u32 s98, s16, 0xb0000
	s_addc_u32 s99, s17, 0
	s_add_i32 s44, 0, 0x18000
	s_add_i32 s45, 0, 0x1c000
	v_add_u32_e32 v140, s44, v175
	v_add_u32_e32 v168, s45, v175
	ds_read_b128 v[128:131], v140
	ds_read_b128 v[132:135], v140 offset:1024
	ds_read_b128 v[136:139], v140 offset:2048
	ds_read_b128 v[140:143], v140 offset:3072
	ds_read_b128 v[144:147], v168
	ds_read_b128 v[148:151], v168 offset:1024
	ds_read_b128 v[164:167], v168 offset:2048
	ds_read_b128 v[168:171], v168 offset:3072
	s_add_u32 s18, s18, 0xb0000
	s_addc_u32 s19, s19, 0
	s_mov_b32 m0, s26
	v_lshl_add_u64 v[224:225], s[98:99], 0, v[152:153]
	s_add_i32 s100, s36, s22
	s_mov_b32 m0, s100
	s_nop 0
	global_load_lds_dwordx4 v[224:225], off
	v_lshl_add_u64 v[224:225], s[98:99], 0, v[154:155]
	s_add_i32 m0, s100, 0x2000
	s_nop 0
	global_load_lds_dwordx4 v[224:225], off
	s_mov_b32 m0, s26
	s_nop 0
	v_lshl_add_u64 v[224:225], s[18:19], 0, v[152:153]
	ds_read_b128 v[186:189], v181 offset:32768
	ds_read_b128 v[192:195], v181 offset:33792
	ds_read_b128 v[196:199], v181 offset:34816
	ds_read_b128 v[200:203], v181 offset:35840
	ds_read_b128 v[204:207], v181 offset:36864
	ds_read_b128 v[208:211], v181 offset:37888
	ds_read_b128 v[212:215], v181 offset:38912
	ds_read_b128 v[216:219], v181 offset:39936
	global_load_lds_dwordx4 v[224:225], off
	v_lshl_add_u64 v[224:225], s[18:19], 0, v[154:155]
	s_mov_b32 m0, s27
	s_nop 0
	global_load_lds_dwordx4 v[224:225], off
	s_waitcnt vmcnt(8)
	s_waitcnt lgkmcnt(0)
	s_barrier
	s_setprio 1
	s_waitcnt lgkmcnt(0)
	v_mfma_f32_16x16x32_bf16 v[124:127], v[128:131], v[186:189], v[124:127]
	v_mfma_f32_16x16x32_bf16 v[120:123], v[136:139], v[186:189], v[120:123]
	v_mfma_f32_16x16x32_bf16 v[116:119], v[128:131], v[196:199], v[116:119]
	v_mfma_f32_16x16x32_bf16 v[112:115], v[136:139], v[196:199], v[112:115]
	v_mfma_f32_16x16x32_bf16 v[100:103], v[128:131], v[204:207], v[100:103]
	v_mfma_f32_16x16x32_bf16 v[88:91], v[136:139], v[204:207], v[88:91]
	v_mfma_f32_16x16x32_bf16 v[84:87], v[128:131], v[212:215], v[84:87]
	v_mfma_f32_16x16x32_bf16 v[76:79], v[136:139], v[212:215], v[76:79]
	v_mfma_f32_16x16x32_bf16 v[124:127], v[132:135], v[192:195], v[124:127]
	v_mfma_f32_16x16x32_bf16 v[120:123], v[140:143], v[192:195], v[120:123]
	v_mfma_f32_16x16x32_bf16 v[116:119], v[132:135], v[200:203], v[116:119]
	v_mfma_f32_16x16x32_bf16 v[112:115], v[140:143], v[200:203], v[112:115]
	v_mfma_f32_16x16x32_bf16 v[100:103], v[132:135], v[208:211], v[100:103]
	v_mfma_f32_16x16x32_bf16 v[88:91], v[140:143], v[208:211], v[88:91]
	v_mfma_f32_16x16x32_bf16 v[84:87], v[132:135], v[216:219], v[84:87]
	v_mfma_f32_16x16x32_bf16 v[76:79], v[140:143], v[216:219], v[76:79]
	s_setprio 0
	s_setprio 1
	v_mfma_f32_16x16x32_bf16 v[108:111], v[144:147], v[186:189], v[108:111]
	v_mfma_f32_16x16x32_bf16 v[104:107], v[164:167], v[186:189], v[104:107]
	v_mfma_f32_16x16x32_bf16 v[96:99], v[144:147], v[196:199], v[96:99]
	v_mfma_f32_16x16x32_bf16 v[92:95], v[164:167], v[196:199], v[92:95]
	v_mfma_f32_16x16x32_bf16 v[80:83], v[144:147], v[204:207], v[80:83]
	v_mfma_f32_16x16x32_bf16 v[72:75], v[164:167], v[204:207], v[72:75]
	v_mfma_f32_16x16x32_bf16 v[68:71], v[144:147], v[212:215], v[68:71]
	v_mfma_f32_16x16x32_bf16 v[64:67], v[164:167], v[212:215], v[64:67]
	v_mfma_f32_16x16x32_bf16 v[108:111], v[148:151], v[192:195], v[108:111]
	v_mfma_f32_16x16x32_bf16 v[104:107], v[168:171], v[192:195], v[104:107]
	v_mfma_f32_16x16x32_bf16 v[96:99], v[148:151], v[200:203], v[96:99]
	v_mfma_f32_16x16x32_bf16 v[92:95], v[168:171], v[200:203], v[92:95]
	v_mfma_f32_16x16x32_bf16 v[80:83], v[148:151], v[208:211], v[80:83]
	v_mfma_f32_16x16x32_bf16 v[72:75], v[168:171], v[208:211], v[72:75]
	v_mfma_f32_16x16x32_bf16 v[68:71], v[148:151], v[216:219], v[68:71]
	v_mfma_f32_16x16x32_bf16 v[64:67], v[168:171], v[216:219], v[64:67]
	s_setprio 0
	s_barrier
	s_add_i32 s18, s44, s22
	v_lshl_add_u64 v[172:173], v[172:173], 0, s[8:9]
	s_mov_b32 m0, s18
	ds_read_b128 v[186:189], v181 offset:49152
	ds_read_b128 v[192:195], v181 offset:50176
	ds_read_b128 v[196:199], v181 offset:51200
	ds_read_b128 v[200:203], v181 offset:52224
	ds_read_b128 v[204:207], v181 offset:53248
	ds_read_b128 v[208:211], v181 offset:54272
	ds_read_b128 v[212:215], v181 offset:55296
	ds_read_b128 v[216:219], v181 offset:56320
	global_load_lds_dwordx4 v[172:173], off
	s_add_i32 m0, s18, 0x2000
	s_add_u32 s16, s16, 0xb0080
	v_lshl_add_u64 v[172:173], v[182:183], 0, s[8:9]
	s_addc_u32 s17, s17, 0
	s_add_i32 s18, s45, s22
	global_load_lds_dwordx4 v[172:173], off
	v_lshl_add_u64 v[172:173], s[16:17], 0, v[152:153]
	s_mov_b32 m0, s18
	s_nop 0
	s_nop 0
	v_lshl_add_u64 v[172:173], s[16:17], 0, v[154:155]
	s_add_i32 m0, s18, 0x2000
	s_nop 0
	s_nop 0
	v_lshl_add_u64 v[172:173], v[220:221], 0, s[8:9]
	s_mov_b32 m0, s33
	s_nop 0
	global_load_lds_dwordx4 v[172:173], off
	v_lshl_add_u64 v[172:173], v[222:223], 0, s[8:9]
	s_mov_b32 m0, s34
	s_nop 0
	global_load_lds_dwordx4 v[172:173], off
	s_waitcnt vmcnt(6)
	s_waitcnt lgkmcnt(0)
	s_barrier
	s_setprio 1
	s_waitcnt lgkmcnt(0)
	v_mfma_f32_16x16x32_bf16 v[60:63], v[128:131], v[186:189], v[60:63]
	v_mfma_f32_16x16x32_bf16 v[56:59], v[136:139], v[186:189], v[56:59]
	v_mfma_f32_16x16x32_bf16 v[52:55], v[128:131], v[196:199], v[52:55]
	v_mfma_f32_16x16x32_bf16 v[48:51], v[136:139], v[196:199], v[48:51]
	v_mfma_f32_16x16x32_bf16 v[40:43], v[128:131], v[204:207], v[40:43]
	v_mfma_f32_16x16x32_bf16 v[28:31], v[136:139], v[204:207], v[28:31]
	v_mfma_f32_16x16x32_bf16 v[16:19], v[128:131], v[212:215], v[16:19]
	v_mfma_f32_16x16x32_bf16 v[8:11], v[136:139], v[212:215], v[8:11]
	v_mfma_f32_16x16x32_bf16 v[60:63], v[132:135], v[192:195], v[60:63]
	v_mfma_f32_16x16x32_bf16 v[56:59], v[140:143], v[192:195], v[56:59]
	v_mfma_f32_16x16x32_bf16 v[52:55], v[132:135], v[200:203], v[52:55]
	v_mfma_f32_16x16x32_bf16 v[48:51], v[140:143], v[200:203], v[48:51]
	v_mfma_f32_16x16x32_bf16 v[40:43], v[132:135], v[208:211], v[40:43]
	v_mfma_f32_16x16x32_bf16 v[28:31], v[140:143], v[208:211], v[28:31]
	v_mfma_f32_16x16x32_bf16 v[16:19], v[132:135], v[216:219], v[16:19]
	v_mfma_f32_16x16x32_bf16 v[8:11], v[140:143], v[216:219], v[8:11]
	s_setprio 0
	s_setprio 1
	v_mfma_f32_16x16x32_bf16 v[44:47], v[144:147], v[186:189], v[44:47]
	v_mfma_f32_16x16x32_bf16 v[36:39], v[164:167], v[186:189], v[36:39]
	v_mfma_f32_16x16x32_bf16 v[32:35], v[144:147], v[196:199], v[32:35]
	v_mfma_f32_16x16x32_bf16 v[24:27], v[164:167], v[196:199], v[24:27]
	v_mfma_f32_16x16x32_bf16 v[20:23], v[144:147], v[204:207], v[20:23]
	v_mfma_f32_16x16x32_bf16 v[12:15], v[164:167], v[204:207], v[12:15]
	v_mfma_f32_16x16x32_bf16 v[4:7], v[144:147], v[212:215], v[4:7]
	v_mfma_f32_16x16x32_bf16 v[0:3], v[164:167], v[212:215], v[0:3]
	v_mfma_f32_16x16x32_bf16 v[44:47], v[148:151], v[192:195], v[44:47]
	v_mfma_f32_16x16x32_bf16 v[36:39], v[168:171], v[192:195], v[36:39]
	v_mfma_f32_16x16x32_bf16 v[32:35], v[148:151], v[200:203], v[32:35]
	v_mfma_f32_16x16x32_bf16 v[24:27], v[168:171], v[200:203], v[24:27]
	v_mfma_f32_16x16x32_bf16 v[20:23], v[148:151], v[208:211], v[20:23]
	v_mfma_f32_16x16x32_bf16 v[12:15], v[168:171], v[208:211], v[12:15]
	v_mfma_f32_16x16x32_bf16 v[4:7], v[148:151], v[216:219], v[4:7]
	v_mfma_f32_16x16x32_bf16 v[0:3], v[168:171], v[216:219], v[0:3]
	s_setprio 0
	s_barrier
	s_add_i32 s43, s43, 2
	s_add_u32 s14, s14, 0x100
	s_addc_u32 s15, s15, 0
	s_add_u32 s41, s41, 0x100
	s_addc_u32 s42, s42, 0
	s_cmp_gt_u32 s43, 41
	s_cbranch_scc0 .LBB0_588
	s_and_b64 vcc, exec, s[10:11]
	s_cbranch_vccz .LBB0_591
	s_barrier

.LBB0_782:
	s_add_u32 s98, s55, 0x3ff80
	s_addc_u32 s99, s56, 0
	ds_read_b128 v[146:149], v178
	ds_read_b128 v[150:153], v178 offset:1024
	ds_read_b128 v[154:157], v178 offset:2048
	ds_read_b128 v[158:161], v178 offset:3072
	ds_read_b128 v[162:165], v179
	ds_read_b128 v[166:169], v179 offset:1024
	ds_read_b128 v[170:173], v179 offset:2048
	ds_read_b128 v[186:189], v179 offset:3072
	s_add_u32 s34, s30, 0xfffc0080
	s_addc_u32 s35, s31, -1
	s_cmp_eq_u32 s57, 12
	s_cselect_b32 s37, s1, s35
	s_cselect_b32 s36, s21, s34
	s_cselect_b32 s35, s23, s56
	s_cselect_b32 s34, s54, s55
	v_lshl_add_u64 v[224:225], s[98:99], 0, v[130:131]
	s_add_i32 m0, s33, 0x1c000
	s_nop 0
	global_load_lds_dwordx4 v[224:225], off
	v_lshl_add_u64 v[224:225], s[98:99], 0, v[134:135]
	s_add_i32 m0, s33, 0x1e000
	s_nop 0
	global_load_lds_dwordx4 v[224:225], off
	v_lshl_add_u64 v[224:225], s[30:31], 0, v[138:139]
	s_add_i32 m0, s29, 0xc000
	ds_read_b128 v[192:195], v180
	ds_read_b128 v[196:199], v180 offset:1024
	ds_read_b128 v[200:203], v180 offset:2048
	ds_read_b128 v[204:207], v180 offset:3072
	ds_read_b128 v[208:211], v180 offset:4096
	ds_read_b128 v[212:215], v180 offset:5120
	ds_read_b128 v[216:219], v180 offset:6144
	ds_read_b128 v[220:223], v180 offset:7168
	global_load_lds_dwordx4 v[224:225], off
	v_lshl_add_u64 v[224:225], s[30:31], 0, v[140:141]
	s_add_i32 m0, s29, 0xe000
	s_nop 0
	global_load_lds_dwordx4 v[224:225], off
	s_waitcnt vmcnt(8)
	s_waitcnt lgkmcnt(0)
	s_barrier
	s_setprio 1
	s_waitcnt lgkmcnt(0)
	v_mfma_f32_16x16x32_bf16 v[124:127], v[146:149], v[192:195], v[124:127]
	v_mfma_f32_16x16x32_bf16 v[120:123], v[154:157], v[192:195], v[120:123]
	v_mfma_f32_16x16x32_bf16 v[116:119], v[146:149], v[200:203], v[116:119]
	v_mfma_f32_16x16x32_bf16 v[108:111], v[154:157], v[200:203], v[108:111]
	v_mfma_f32_16x16x32_bf16 v[100:103], v[146:149], v[208:211], v[100:103]
	v_mfma_f32_16x16x32_bf16 v[92:95], v[154:157], v[208:211], v[92:95]
	v_mfma_f32_16x16x32_bf16 v[84:87], v[146:149], v[216:219], v[84:87]
	v_mfma_f32_16x16x32_bf16 v[76:79], v[154:157], v[216:219], v[76:79]
	v_mfma_f32_16x16x32_bf16 v[124:127], v[150:153], v[196:199], v[124:127]
	v_mfma_f32_16x16x32_bf16 v[120:123], v[158:161], v[196:199], v[120:123]
	v_mfma_f32_16x16x32_bf16 v[116:119], v[150:153], v[204:207], v[116:119]
	v_mfma_f32_16x16x32_bf16 v[108:111], v[158:161], v[204:207], v[108:111]
	v_mfma_f32_16x16x32_bf16 v[100:103], v[150:153], v[212:215], v[100:103]
	v_mfma_f32_16x16x32_bf16 v[92:95], v[158:161], v[212:215], v[92:95]
	v_mfma_f32_16x16x32_bf16 v[84:87], v[150:153], v[220:223], v[84:87]
	v_mfma_f32_16x16x32_bf16 v[76:79], v[158:161], v[220:223], v[76:79]
	s_setprio 0
	s_setprio 1
	v_mfma_f32_16x16x32_bf16 v[112:115], v[162:165], v[192:195], v[112:115]
	v_mfma_f32_16x16x32_bf16 v[104:107], v[170:173], v[192:195], v[104:107]
	v_mfma_f32_16x16x32_bf16 v[96:99], v[162:165], v[200:203], v[96:99]
	v_mfma_f32_16x16x32_bf16 v[88:91], v[170:173], v[200:203], v[88:91]
	v_mfma_f32_16x16x32_bf16 v[80:83], v[162:165], v[208:211], v[80:83]
	v_mfma_f32_16x16x32_bf16 v[72:75], v[170:173], v[208:211], v[72:75]
	v_mfma_f32_16x16x32_bf16 v[68:71], v[162:165], v[216:219], v[68:71]
	v_mfma_f32_16x16x32_bf16 v[64:67], v[170:173], v[216:219], v[64:67]
	v_mfma_f32_16x16x32_bf16 v[112:115], v[166:169], v[196:199], v[112:115]
	v_mfma_f32_16x16x32_bf16 v[104:107], v[186:189], v[196:199], v[104:107]
	v_mfma_f32_16x16x32_bf16 v[96:99], v[166:169], v[204:207], v[96:99]
	v_mfma_f32_16x16x32_bf16 v[88:91], v[186:189], v[204:207], v[88:91]
	v_mfma_f32_16x16x32_bf16 v[80:83], v[166:169], v[212:215], v[80:83]
	v_mfma_f32_16x16x32_bf16 v[72:75], v[186:189], v[212:215], v[72:75]
	v_mfma_f32_16x16x32_bf16 v[68:71], v[166:169], v[220:223], v[68:71]
	v_mfma_f32_16x16x32_bf16 v[64:67], v[186:189], v[220:223], v[64:67]
	s_setprio 0
	s_barrier
	s_add_i32 s58, s47, s33
	v_lshl_add_u64 v[224:225], s[34:35], 0, v[130:131]
	s_mov_b32 m0, s58
	ds_read_b128 v[192:195], v180 offset:16384
	ds_read_b128 v[196:199], v180 offset:17408
	ds_read_b128 v[200:203], v180 offset:18432
	ds_read_b128 v[204:207], v180 offset:19456
	ds_read_b128 v[208:211], v180 offset:20480
	ds_read_b128 v[212:215], v180 offset:21504
	ds_read_b128 v[216:219], v180 offset:22528
	ds_read_b128 v[220:223], v180 offset:23552
	global_load_lds_dwordx4 v[224:225], off
	s_add_i32 m0, s58, 0x2000
	s_add_u32 s58, s34, 0x40000
	v_lshl_add_u64 v[226:227], s[34:35], 0, v[134:135]
	s_addc_u32 s59, s35, 0
	s_add_i32 s60, s48, s33
	global_load_lds_dwordx4 v[226:227], off
	v_lshl_add_u64 v[228:229], s[58:59], 0, v[130:131]
	s_mov_b32 m0, s60
	v_lshl_add_u64 v[230:231], s[36:37], 0, v[132:133]
	s_nop 0
	v_lshl_add_u64 v[228:229], s[58:59], 0, v[134:135]
	s_add_i32 m0, s60, 0x2000
	s_nop 0
	s_nop 0
	v_lshl_add_u64 v[228:229], s[36:37], 0, v[128:129]
	s_mov_b32 m0, s29
	s_nop 0
	global_load_lds_dwordx4 v[228:229], off
	s_mov_b32 m0, s40
	s_nop 0
	global_load_lds_dwordx4 v[230:231], off
	s_waitcnt vmcnt(6)
	s_waitcnt lgkmcnt(0)
	s_barrier
	s_setprio 1
	s_waitcnt lgkmcnt(0)
	v_mfma_f32_16x16x32_bf16 v[60:63], v[146:149], v[192:195], v[60:63]
	v_mfma_f32_16x16x32_bf16 v[56:59], v[154:157], v[192:195], v[56:59]
	v_mfma_f32_16x16x32_bf16 v[52:55], v[146:149], v[200:203], v[52:55]
	v_mfma_f32_16x16x32_bf16 v[44:47], v[154:157], v[200:203], v[44:47]
	v_mfma_f32_16x16x32_bf16 v[36:39], v[146:149], v[208:211], v[36:39]
	v_mfma_f32_16x16x32_bf16 v[28:31], v[154:157], v[208:211], v[28:31]
	v_mfma_f32_16x16x32_bf16 v[20:23], v[146:149], v[216:219], v[20:23]
	v_mfma_f32_16x16x32_bf16 v[12:15], v[154:157], v[216:219], v[12:15]
	v_mfma_f32_16x16x32_bf16 v[60:63], v[150:153], v[196:199], v[60:63]
	v_mfma_f32_16x16x32_bf16 v[56:59], v[158:161], v[196:199], v[56:59]
	v_mfma_f32_16x16x32_bf16 v[52:55], v[150:153], v[204:207], v[52:55]
	v_mfma_f32_16x16x32_bf16 v[44:47], v[158:161], v[204:207], v[44:47]
	v_mfma_f32_16x16x32_bf16 v[36:39], v[150:153], v[212:215], v[36:39]
	v_mfma_f32_16x16x32_bf16 v[28:31], v[158:161], v[212:215], v[28:31]
	v_mfma_f32_16x16x32_bf16 v[20:23], v[150:153], v[220:223], v[20:23]
	v_mfma_f32_16x16x32_bf16 v[12:15], v[158:161], v[220:223], v[12:15]
	s_setprio 0
	s_setprio 1
	v_mfma_f32_16x16x32_bf16 v[48:51], v[162:165], v[192:195], v[48:51]
	v_mfma_f32_16x16x32_bf16 v[40:43], v[170:173], v[192:195], v[40:43]
	v_mfma_f32_16x16x32_bf16 v[32:35], v[162:165], v[200:203], v[32:35]
	v_mfma_f32_16x16x32_bf16 v[24:27], v[170:173], v[200:203], v[24:27]
	v_mfma_f32_16x16x32_bf16 v[16:19], v[162:165], v[208:211], v[16:19]
	v_mfma_f32_16x16x32_bf16 v[8:11], v[170:173], v[208:211], v[8:11]
	v_mfma_f32_16x16x32_bf16 v[4:7], v[162:165], v[216:219], v[4:7]
	v_mfma_f32_16x16x32_bf16 v[0:3], v[170:173], v[216:219], v[0:3]
	v_mfma_f32_16x16x32_bf16 v[48:51], v[166:169], v[196:199], v[48:51]
	v_mfma_f32_16x16x32_bf16 v[40:43], v[186:189], v[196:199], v[40:43]
	v_mfma_f32_16x16x32_bf16 v[32:35], v[166:169], v[204:207], v[32:35]
	v_mfma_f32_16x16x32_bf16 v[24:27], v[186:189], v[204:207], v[24:27]
	v_mfma_f32_16x16x32_bf16 v[16:19], v[166:169], v[212:215], v[16:19]
	v_mfma_f32_16x16x32_bf16 v[8:11], v[186:189], v[212:215], v[8:11]
	v_mfma_f32_16x16x32_bf16 v[4:7], v[166:169], v[220:223], v[4:7]
	v_mfma_f32_16x16x32_bf16 v[0:3], v[186:189], v[220:223], v[0:3]
	s_setprio 0
	s_barrier
	s_add_u32 s98, s34, 0x40000
	s_addc_u32 s99, s35, 0
	s_add_i32 s58, 0, 0x18000
	v_add_u32_e32 v136, s58, v175
	s_add_i32 s59, 0, 0x1c000
	ds_read_b128 v[146:149], v136
	ds_read_b128 v[150:153], v136 offset:1024
	ds_read_b128 v[154:157], v136 offset:2048
	ds_read_b128 v[158:161], v136 offset:3072
	v_add_u32_e32 v136, s59, v175
	ds_read_b128 v[162:165], v136
	ds_read_b128 v[166:169], v136 offset:1024
	ds_read_b128 v[170:173], v136 offset:2048
	ds_read_b128 v[186:189], v136 offset:3072
	s_add_u32 s36, s36, 0x40000
	s_addc_u32 s37, s37, 0
	s_mov_b32 m0, s41
	v_lshl_add_u64 v[232:233], s[98:99], 0, v[130:131]
	s_add_i32 s100, s48, s33
	s_mov_b32 m0, s100
	s_nop 0
	global_load_lds_dwordx4 v[232:233], off
	v_lshl_add_u64 v[232:233], s[98:99], 0, v[134:135]
	s_add_i32 m0, s100, 0x2000
	s_nop 0
	global_load_lds_dwordx4 v[232:233], off
	s_mov_b32 m0, s41
	s_nop 0
	v_lshl_add_u64 v[232:233], s[36:37], 0, v[128:129]
	ds_read_b128 v[192:195], v180 offset:32768
	ds_read_b128 v[196:199], v180 offset:33792
	ds_read_b128 v[200:203], v180 offset:34816
	ds_read_b128 v[204:207], v180 offset:35840
	ds_read_b128 v[208:211], v180 offset:36864
	ds_read_b128 v[212:215], v180 offset:37888
	ds_read_b128 v[216:219], v180 offset:38912
	ds_read_b128 v[220:223], v180 offset:39936
	global_load_lds_dwordx4 v[232:233], off
	v_lshl_add_u64 v[232:233], s[36:37], 0, v[132:133]
	s_mov_b32 m0, s42
	s_nop 0
	global_load_lds_dwordx4 v[232:233], off
	s_waitcnt vmcnt(8)
	s_waitcnt lgkmcnt(0)
	s_barrier
	s_setprio 1
	s_waitcnt lgkmcnt(0)
	v_mfma_f32_16x16x32_bf16 v[124:127], v[146:149], v[192:195], v[124:127]
	v_mfma_f32_16x16x32_bf16 v[120:123], v[154:157], v[192:195], v[120:123]
	v_mfma_f32_16x16x32_bf16 v[116:119], v[146:149], v[200:203], v[116:119]
	v_mfma_f32_16x16x32_bf16 v[108:111], v[154:157], v[200:203], v[108:111]
	v_mfma_f32_16x16x32_bf16 v[100:103], v[146:149], v[208:211], v[100:103]
	v_mfma_f32_16x16x32_bf16 v[92:95], v[154:157], v[208:211], v[92:95]
	v_mfma_f32_16x16x32_bf16 v[84:87], v[146:149], v[216:219], v[84:87]
	v_mfma_f32_16x16x32_bf16 v[76:79], v[154:157], v[216:219], v[76:79]
	v_mfma_f32_16x16x32_bf16 v[124:127], v[150:153], v[196:199], v[124:127]
	v_mfma_f32_16x16x32_bf16 v[120:123], v[158:161], v[196:199], v[120:123]
	v_mfma_f32_16x16x32_bf16 v[116:119], v[150:153], v[204:207], v[116:119]
	v_mfma_f32_16x16x32_bf16 v[108:111], v[158:161], v[204:207], v[108:111]
	v_mfma_f32_16x16x32_bf16 v[100:103], v[150:153], v[212:215], v[100:103]
	v_mfma_f32_16x16x32_bf16 v[92:95], v[158:161], v[212:215], v[92:95]
	v_mfma_f32_16x16x32_bf16 v[84:87], v[150:153], v[220:223], v[84:87]
	v_mfma_f32_16x16x32_bf16 v[76:79], v[158:161], v[220:223], v[76:79]
	s_setprio 0
	s_setprio 1
	v_mfma_f32_16x16x32_bf16 v[112:115], v[162:165], v[192:195], v[112:115]
	v_mfma_f32_16x16x32_bf16 v[104:107], v[170:173], v[192:195], v[104:107]
	v_mfma_f32_16x16x32_bf16 v[96:99], v[162:165], v[200:203], v[96:99]
	v_mfma_f32_16x16x32_bf16 v[88:91], v[170:173], v[200:203], v[88:91]
	v_mfma_f32_16x16x32_bf16 v[80:83], v[162:165], v[208:211], v[80:83]
	v_mfma_f32_16x16x32_bf16 v[72:75], v[170:173], v[208:211], v[72:75]
	v_mfma_f32_16x16x32_bf16 v[68:71], v[162:165], v[216:219], v[68:71]
	v_mfma_f32_16x16x32_bf16 v[64:67], v[170:173], v[216:219], v[64:67]
	v_mfma_f32_16x16x32_bf16 v[112:115], v[166:169], v[196:199], v[112:115]
	v_mfma_f32_16x16x32_bf16 v[104:107], v[186:189], v[196:199], v[104:107]
	v_mfma_f32_16x16x32_bf16 v[96:99], v[166:169], v[204:207], v[96:99]
	v_mfma_f32_16x16x32_bf16 v[88:91], v[186:189], v[204:207], v[88:91]
	v_mfma_f32_16x16x32_bf16 v[80:83], v[166:169], v[212:215], v[80:83]
	v_mfma_f32_16x16x32_bf16 v[72:75], v[186:189], v[212:215], v[72:75]
	v_mfma_f32_16x16x32_bf16 v[68:71], v[166:169], v[220:223], v[68:71]
	v_mfma_f32_16x16x32_bf16 v[64:67], v[186:189], v[220:223], v[64:67]
	s_setprio 0
	s_barrier
	s_add_i32 s36, s58, s33
	v_lshl_add_u64 v[224:225], v[224:225], 0, s[10:11]
	s_mov_b32 m0, s36
	ds_read_b128 v[192:195], v180 offset:49152
	ds_read_b128 v[196:199], v180 offset:50176
	ds_read_b128 v[200:203], v180 offset:51200
	ds_read_b128 v[204:207], v180 offset:52224
	ds_read_b128 v[208:211], v180 offset:53248
	ds_read_b128 v[212:215], v180 offset:54272
	ds_read_b128 v[216:219], v180 offset:55296
	ds_read_b128 v[220:223], v180 offset:56320
	global_load_lds_dwordx4 v[224:225], off
	s_add_i32 m0, s36, 0x2000
	s_add_u32 s34, s34, 0x40080
	v_lshl_add_u64 v[224:225], v[226:227], 0, s[10:11]
	s_addc_u32 s35, s35, 0
	s_add_i32 s36, s59, s33
	global_load_lds_dwordx4 v[224:225], off
	v_lshl_add_u64 v[224:225], s[34:35], 0, v[130:131]
	s_mov_b32 m0, s36
	s_nop 0
	s_nop 0
	v_lshl_add_u64 v[224:225], s[34:35], 0, v[134:135]
	s_add_i32 m0, s36, 0x2000
	s_nop 0
	s_nop 0
	v_lshl_add_u64 v[224:225], v[228:229], 0, s[10:11]
	s_mov_b32 m0, s45
	s_nop 0
	global_load_lds_dwordx4 v[224:225], off
	v_lshl_add_u64 v[224:225], v[230:231], 0, s[10:11]
	s_mov_b32 m0, s46
	s_nop 0
	global_load_lds_dwordx4 v[224:225], off
	s_waitcnt vmcnt(6)
	s_waitcnt lgkmcnt(0)
	s_barrier
	s_setprio 1
	s_waitcnt lgkmcnt(0)
	v_mfma_f32_16x16x32_bf16 v[60:63], v[146:149], v[192:195], v[60:63]
	v_mfma_f32_16x16x32_bf16 v[56:59], v[154:157], v[192:195], v[56:59]
	v_mfma_f32_16x16x32_bf16 v[52:55], v[146:149], v[200:203], v[52:55]
	v_mfma_f32_16x16x32_bf16 v[44:47], v[154:157], v[200:203], v[44:47]
	v_mfma_f32_16x16x32_bf16 v[36:39], v[146:149], v[208:211], v[36:39]
	v_mfma_f32_16x16x32_bf16 v[28:31], v[154:157], v[208:211], v[28:31]
	v_mfma_f32_16x16x32_bf16 v[20:23], v[146:149], v[216:219], v[20:23]
	v_mfma_f32_16x16x32_bf16 v[12:15], v[154:157], v[216:219], v[12:15]
	v_mfma_f32_16x16x32_bf16 v[60:63], v[150:153], v[196:199], v[60:63]
	v_mfma_f32_16x16x32_bf16 v[56:59], v[158:161], v[196:199], v[56:59]
	v_mfma_f32_16x16x32_bf16 v[52:55], v[150:153], v[204:207], v[52:55]
	v_mfma_f32_16x16x32_bf16 v[44:47], v[158:161], v[204:207], v[44:47]
	v_mfma_f32_16x16x32_bf16 v[36:39], v[150:153], v[212:215], v[36:39]
	v_mfma_f32_16x16x32_bf16 v[28:31], v[158:161], v[212:215], v[28:31]
	v_mfma_f32_16x16x32_bf16 v[20:23], v[150:153], v[220:223], v[20:23]
	v_mfma_f32_16x16x32_bf16 v[12:15], v[158:161], v[220:223], v[12:15]
	s_setprio 0
	s_setprio 1
	v_mfma_f32_16x16x32_bf16 v[48:51], v[162:165], v[192:195], v[48:51]
	v_mfma_f32_16x16x32_bf16 v[40:43], v[170:173], v[192:195], v[40:43]
	v_mfma_f32_16x16x32_bf16 v[32:35], v[162:165], v[200:203], v[32:35]
	v_mfma_f32_16x16x32_bf16 v[24:27], v[170:173], v[200:203], v[24:27]
	v_mfma_f32_16x16x32_bf16 v[16:19], v[162:165], v[208:211], v[16:19]
	v_mfma_f32_16x16x32_bf16 v[8:11], v[170:173], v[208:211], v[8:11]
	v_mfma_f32_16x16x32_bf16 v[4:7], v[162:165], v[216:219], v[4:7]
	v_mfma_f32_16x16x32_bf16 v[0:3], v[170:173], v[216:219], v[0:3]
	v_mfma_f32_16x16x32_bf16 v[48:51], v[166:169], v[196:199], v[48:51]
	v_mfma_f32_16x16x32_bf16 v[40:43], v[186:189], v[196:199], v[40:43]
	v_mfma_f32_16x16x32_bf16 v[32:35], v[166:169], v[204:207], v[32:35]
	v_mfma_f32_16x16x32_bf16 v[24:27], v[186:189], v[204:207], v[24:27]
	v_mfma_f32_16x16x32_bf16 v[16:19], v[166:169], v[212:215], v[16:19]
	v_mfma_f32_16x16x32_bf16 v[8:11], v[186:189], v[212:215], v[8:11]
	v_mfma_f32_16x16x32_bf16 v[4:7], v[166:169], v[220:223], v[4:7]
	v_mfma_f32_16x16x32_bf16 v[0:3], v[186:189], v[220:223], v[0:3]
	s_setprio 0
	s_barrier
	s_add_i32 s57, s57, 2
	s_add_u32 s30, s30, 0x100
	s_addc_u32 s31, s31, 0
	s_add_u32 s55, s55, 0x100
	s_addc_u32 s56, s56, 0
	s_cmp_gt_u32 s57, 13
	s_cbranch_scc0 .LBB0_782
	s_and_b64 vcc, exec, s[12:13]
	s_cbranch_vccz .LBB0_785
	s_barrier

.LBB0_980:
	s_add_u32 s98, s53, 0x3ff80
	s_addc_u32 s99, s54, 0
	ds_read_b128 v[80:83], v194
	ds_read_b128 v[84:87], v194 offset:1024
	ds_read_b128 v[88:91], v194 offset:2048
	ds_read_b128 v[96:99], v194 offset:3072
	ds_read_b128 v[144:147], v195
	ds_read_b128 v[148:151], v195 offset:1024
	ds_read_b128 v[152:155], v195 offset:2048
	ds_read_b128 v[156:159], v195 offset:3072
	s_add_u32 s30, s28, 0xfffc0080
	s_addc_u32 s31, s29, -1
	s_cmp_eq_u32 s55, 12
	s_cselect_b32 s35, s19, s31
	s_cselect_b32 s34, s25, s30
	s_cselect_b32 s31, s17, s54
	s_cselect_b32 s30, s52, s53
	v_lshl_add_u64 v[188:189], s[98:99], 0, v[160:161]
	s_add_i32 m0, s37, 0x1c000
	s_nop 0
	global_load_lds_dwordx4 v[188:189], off
	v_lshl_add_u64 v[188:189], s[98:99], 0, v[162:163]
	s_add_i32 m0, s37, 0x1e000
	s_nop 0
	global_load_lds_dwordx4 v[188:189], off
	v_lshl_add_u64 v[188:189], s[28:29], 0, v[164:165]
	s_add_i32 m0, s27, 0xc000
	ds_read_b128 v[172:175], v196
	ds_read_b128 v[176:179], v196 offset:1024
	ds_read_b128 v[180:183], v196 offset:2048
	ds_read_b128 v[184:187], v196 offset:3072
	ds_read_b128 v[198:201], v196 offset:4096
	ds_read_b128 v[202:205], v196 offset:5120
	ds_read_b128 v[206:209], v196 offset:6144
	ds_read_b128 v[210:213], v196 offset:7168
	global_load_lds_dwordx4 v[188:189], off
	v_lshl_add_u64 v[188:189], s[28:29], 0, v[166:167]
	s_add_i32 m0, s27, 0xe000
	s_nop 0
	global_load_lds_dwordx4 v[188:189], off
	s_waitcnt vmcnt(8)
	s_waitcnt lgkmcnt(0)
	s_barrier
	s_setprio 1
	s_waitcnt lgkmcnt(0)
	v_mfma_f32_16x16x32_bf16 v[140:143], v[80:83], v[172:175], v[140:143]
	v_mfma_f32_16x16x32_bf16 v[136:139], v[88:91], v[172:175], v[136:139]
	v_mfma_f32_16x16x32_bf16 v[124:127], v[80:83], v[180:183], v[124:127]
	v_mfma_f32_16x16x32_bf16 v[120:123], v[88:91], v[180:183], v[120:123]
	v_mfma_f32_16x16x32_bf16 v[108:111], v[80:83], v[198:201], v[108:111]
	v_mfma_f32_16x16x32_bf16 v[104:107], v[88:91], v[198:201], v[104:107]
	v_mfma_f32_16x16x32_bf16 v[76:79], v[80:83], v[206:209], v[76:79]
	v_mfma_f32_16x16x32_bf16 v[72:75], v[88:91], v[206:209], v[72:75]
	v_mfma_f32_16x16x32_bf16 v[140:143], v[84:87], v[176:179], v[140:143]
	v_mfma_f32_16x16x32_bf16 v[136:139], v[96:99], v[176:179], v[136:139]
	v_mfma_f32_16x16x32_bf16 v[124:127], v[84:87], v[184:187], v[124:127]
	v_mfma_f32_16x16x32_bf16 v[120:123], v[96:99], v[184:187], v[120:123]
	v_mfma_f32_16x16x32_bf16 v[108:111], v[84:87], v[202:205], v[108:111]
	v_mfma_f32_16x16x32_bf16 v[104:107], v[96:99], v[202:205], v[104:107]
	v_mfma_f32_16x16x32_bf16 v[76:79], v[84:87], v[210:213], v[76:79]
	v_mfma_f32_16x16x32_bf16 v[72:75], v[96:99], v[210:213], v[72:75]
	s_setprio 0
	s_setprio 1
	v_mfma_f32_16x16x32_bf16 v[132:135], v[144:147], v[172:175], v[132:135]
	v_mfma_f32_16x16x32_bf16 v[128:131], v[152:155], v[172:175], v[128:131]
	v_mfma_f32_16x16x32_bf16 v[116:119], v[144:147], v[180:183], v[116:119]
	v_mfma_f32_16x16x32_bf16 v[112:115], v[152:155], v[180:183], v[112:115]
	v_mfma_f32_16x16x32_bf16 v[100:103], v[144:147], v[198:201], v[100:103]
	v_mfma_f32_16x16x32_bf16 v[92:95], v[152:155], v[198:201], v[92:95]
	v_mfma_f32_16x16x32_bf16 v[68:71], v[144:147], v[206:209], v[68:71]
	v_mfma_f32_16x16x32_bf16 v[64:67], v[152:155], v[206:209], v[64:67]
	v_mfma_f32_16x16x32_bf16 v[132:135], v[148:151], v[176:179], v[132:135]
	v_mfma_f32_16x16x32_bf16 v[128:131], v[156:159], v[176:179], v[128:131]
	v_mfma_f32_16x16x32_bf16 v[116:119], v[148:151], v[184:187], v[116:119]
	v_mfma_f32_16x16x32_bf16 v[112:115], v[156:159], v[184:187], v[112:115]
	v_mfma_f32_16x16x32_bf16 v[100:103], v[148:151], v[202:205], v[100:103]
	v_mfma_f32_16x16x32_bf16 v[92:95], v[156:159], v[202:205], v[92:95]
	v_mfma_f32_16x16x32_bf16 v[68:71], v[148:151], v[210:213], v[68:71]
	v_mfma_f32_16x16x32_bf16 v[64:67], v[156:159], v[210:213], v[64:67]
	s_setprio 0
	s_barrier
	s_add_i32 s56, s50, s37
	v_lshl_add_u64 v[188:189], s[30:31], 0, v[160:161]
	s_mov_b32 m0, s56
	ds_read_b128 v[172:175], v196 offset:16384
	ds_read_b128 v[176:179], v196 offset:17408
	ds_read_b128 v[180:183], v196 offset:18432
	ds_read_b128 v[184:187], v196 offset:19456
	ds_read_b128 v[198:201], v196 offset:20480
	ds_read_b128 v[202:205], v196 offset:21504
	ds_read_b128 v[206:209], v196 offset:22528
	ds_read_b128 v[210:213], v196 offset:23552
	global_load_lds_dwordx4 v[188:189], off
	s_add_i32 m0, s56, 0x2000
	s_add_u32 s56, s30, 0x40000
	v_lshl_add_u64 v[214:215], s[30:31], 0, v[162:163]
	s_addc_u32 s57, s31, 0
	s_add_i32 s58, s51, s37
	global_load_lds_dwordx4 v[214:215], off
	v_lshl_add_u64 v[216:217], s[56:57], 0, v[160:161]
	s_mov_b32 m0, s58
	v_lshl_add_u64 v[218:219], s[34:35], 0, v[162:163]
	s_nop 0
	v_lshl_add_u64 v[216:217], s[56:57], 0, v[162:163]
	s_add_i32 m0, s58, 0x2000
	s_nop 0
	s_nop 0
	v_lshl_add_u64 v[216:217], s[34:35], 0, v[160:161]
	s_mov_b32 m0, s27
	s_nop 0
	global_load_lds_dwordx4 v[216:217], off
	s_mov_b32 m0, s38
	s_nop 0
	global_load_lds_dwordx4 v[218:219], off
	s_waitcnt vmcnt(6)
	s_waitcnt lgkmcnt(0)
	s_barrier
	s_setprio 1
	s_waitcnt lgkmcnt(0)
	v_mfma_f32_16x16x32_bf16 v[60:63], v[80:83], v[172:175], v[60:63]
	v_mfma_f32_16x16x32_bf16 v[56:59], v[88:91], v[172:175], v[56:59]
	v_mfma_f32_16x16x32_bf16 v[44:47], v[80:83], v[180:183], v[44:47]
	v_mfma_f32_16x16x32_bf16 v[40:43], v[88:91], v[180:183], v[40:43]
	v_mfma_f32_16x16x32_bf16 v[28:31], v[80:83], v[198:201], v[28:31]
	v_mfma_f32_16x16x32_bf16 v[24:27], v[88:91], v[198:201], v[24:27]
	v_mfma_f32_16x16x32_bf16 v[12:15], v[80:83], v[206:209], v[12:15]
	v_mfma_f32_16x16x32_bf16 v[8:11], v[88:91], v[206:209], v[8:11]
	v_mfma_f32_16x16x32_bf16 v[60:63], v[84:87], v[176:179], v[60:63]
	v_mfma_f32_16x16x32_bf16 v[56:59], v[96:99], v[176:179], v[56:59]
	v_mfma_f32_16x16x32_bf16 v[44:47], v[84:87], v[184:187], v[44:47]
	v_mfma_f32_16x16x32_bf16 v[40:43], v[96:99], v[184:187], v[40:43]
	v_mfma_f32_16x16x32_bf16 v[28:31], v[84:87], v[202:205], v[28:31]
	v_mfma_f32_16x16x32_bf16 v[24:27], v[96:99], v[202:205], v[24:27]
	v_mfma_f32_16x16x32_bf16 v[12:15], v[84:87], v[210:213], v[12:15]
	v_mfma_f32_16x16x32_bf16 v[8:11], v[96:99], v[210:213], v[8:11]
	s_setprio 0
	s_setprio 1
	v_mfma_f32_16x16x32_bf16 v[52:55], v[144:147], v[172:175], v[52:55]
	v_mfma_f32_16x16x32_bf16 v[48:51], v[152:155], v[172:175], v[48:51]
	v_mfma_f32_16x16x32_bf16 v[36:39], v[144:147], v[180:183], v[36:39]
	v_mfma_f32_16x16x32_bf16 v[32:35], v[152:155], v[180:183], v[32:35]
	v_mfma_f32_16x16x32_bf16 v[20:23], v[144:147], v[198:201], v[20:23]
	v_mfma_f32_16x16x32_bf16 v[16:19], v[152:155], v[198:201], v[16:19]
	v_mfma_f32_16x16x32_bf16 v[4:7], v[144:147], v[206:209], v[4:7]
	v_mfma_f32_16x16x32_bf16 v[0:3], v[152:155], v[206:209], v[0:3]
	v_mfma_f32_16x16x32_bf16 v[52:55], v[148:151], v[176:179], v[52:55]
	v_mfma_f32_16x16x32_bf16 v[48:51], v[156:159], v[176:179], v[48:51]
	v_mfma_f32_16x16x32_bf16 v[36:39], v[148:151], v[184:187], v[36:39]
	v_mfma_f32_16x16x32_bf16 v[32:35], v[156:159], v[184:187], v[32:35]
	v_mfma_f32_16x16x32_bf16 v[20:23], v[148:151], v[202:205], v[20:23]
	v_mfma_f32_16x16x32_bf16 v[16:19], v[156:159], v[202:205], v[16:19]
	v_mfma_f32_16x16x32_bf16 v[4:7], v[148:151], v[210:213], v[4:7]
	v_mfma_f32_16x16x32_bf16 v[0:3], v[156:159], v[210:213], v[0:3]
	s_setprio 0
	s_barrier
	s_add_u32 s98, s30, 0x40000
	s_addc_u32 s99, s31, 0
	s_add_i32 s56, 0, 0x18000
	s_add_i32 s57, 0, 0x1c000
	v_add_u32_e32 v96, s56, v192
	v_add_u32_e32 v156, s57, v192
	ds_read_b128 v[80:83], v96
	ds_read_b128 v[84:87], v96 offset:1024
	ds_read_b128 v[88:91], v96 offset:2048
	ds_read_b128 v[96:99], v96 offset:3072
	ds_read_b128 v[144:147], v156
	ds_read_b128 v[148:151], v156 offset:1024
	ds_read_b128 v[152:155], v156 offset:2048
	ds_read_b128 v[156:159], v156 offset:3072
	s_add_u32 s34, s34, 0x40000
	s_addc_u32 s35, s35, 0
	s_mov_b32 m0, s39
	v_lshl_add_u64 v[220:221], s[98:99], 0, v[160:161]
	s_add_i32 s100, s51, s37
	s_mov_b32 m0, s100
	s_nop 0
	global_load_lds_dwordx4 v[220:221], off
	v_lshl_add_u64 v[220:221], s[98:99], 0, v[162:163]
	s_add_i32 m0, s100, 0x2000
	s_nop 0
	global_load_lds_dwordx4 v[220:221], off
	s_mov_b32 m0, s39
	s_nop 0
	v_lshl_add_u64 v[220:221], s[34:35], 0, v[160:161]
	ds_read_b128 v[172:175], v196 offset:32768
	ds_read_b128 v[176:179], v196 offset:33792
	ds_read_b128 v[180:183], v196 offset:34816
	ds_read_b128 v[184:187], v196 offset:35840
	ds_read_b128 v[198:201], v196 offset:36864
	ds_read_b128 v[202:205], v196 offset:37888
	ds_read_b128 v[206:209], v196 offset:38912
	ds_read_b128 v[210:213], v196 offset:39936
	global_load_lds_dwordx4 v[220:221], off
	v_lshl_add_u64 v[220:221], s[34:35], 0, v[162:163]
	s_mov_b32 m0, s40
	s_nop 0
	global_load_lds_dwordx4 v[220:221], off
	s_waitcnt vmcnt(8)
	s_waitcnt lgkmcnt(0)
	s_barrier
	s_setprio 1
	s_waitcnt lgkmcnt(0)
	v_mfma_f32_16x16x32_bf16 v[140:143], v[80:83], v[172:175], v[140:143]
	v_mfma_f32_16x16x32_bf16 v[136:139], v[88:91], v[172:175], v[136:139]
	v_mfma_f32_16x16x32_bf16 v[124:127], v[80:83], v[180:183], v[124:127]
	v_mfma_f32_16x16x32_bf16 v[120:123], v[88:91], v[180:183], v[120:123]
	v_mfma_f32_16x16x32_bf16 v[108:111], v[80:83], v[198:201], v[108:111]
	v_mfma_f32_16x16x32_bf16 v[104:107], v[88:91], v[198:201], v[104:107]
	v_mfma_f32_16x16x32_bf16 v[76:79], v[80:83], v[206:209], v[76:79]
	v_mfma_f32_16x16x32_bf16 v[72:75], v[88:91], v[206:209], v[72:75]
	v_mfma_f32_16x16x32_bf16 v[140:143], v[84:87], v[176:179], v[140:143]
	v_mfma_f32_16x16x32_bf16 v[136:139], v[96:99], v[176:179], v[136:139]
	v_mfma_f32_16x16x32_bf16 v[124:127], v[84:87], v[184:187], v[124:127]
	v_mfma_f32_16x16x32_bf16 v[120:123], v[96:99], v[184:187], v[120:123]
	v_mfma_f32_16x16x32_bf16 v[108:111], v[84:87], v[202:205], v[108:111]
	v_mfma_f32_16x16x32_bf16 v[104:107], v[96:99], v[202:205], v[104:107]
	v_mfma_f32_16x16x32_bf16 v[76:79], v[84:87], v[210:213], v[76:79]
	v_mfma_f32_16x16x32_bf16 v[72:75], v[96:99], v[210:213], v[72:75]
	s_setprio 0
	s_setprio 1
	v_mfma_f32_16x16x32_bf16 v[132:135], v[144:147], v[172:175], v[132:135]
	v_mfma_f32_16x16x32_bf16 v[128:131], v[152:155], v[172:175], v[128:131]
	v_mfma_f32_16x16x32_bf16 v[116:119], v[144:147], v[180:183], v[116:119]
	v_mfma_f32_16x16x32_bf16 v[112:115], v[152:155], v[180:183], v[112:115]
	v_mfma_f32_16x16x32_bf16 v[100:103], v[144:147], v[198:201], v[100:103]
	v_mfma_f32_16x16x32_bf16 v[92:95], v[152:155], v[198:201], v[92:95]
	v_mfma_f32_16x16x32_bf16 v[68:71], v[144:147], v[206:209], v[68:71]
	v_mfma_f32_16x16x32_bf16 v[64:67], v[152:155], v[206:209], v[64:67]
	v_mfma_f32_16x16x32_bf16 v[132:135], v[148:151], v[176:179], v[132:135]
	v_mfma_f32_16x16x32_bf16 v[128:131], v[156:159], v[176:179], v[128:131]
	v_mfma_f32_16x16x32_bf16 v[116:119], v[148:151], v[184:187], v[116:119]
	v_mfma_f32_16x16x32_bf16 v[112:115], v[156:159], v[184:187], v[112:115]
	v_mfma_f32_16x16x32_bf16 v[100:103], v[148:151], v[202:205], v[100:103]
	v_mfma_f32_16x16x32_bf16 v[92:95], v[156:159], v[202:205], v[92:95]
	v_mfma_f32_16x16x32_bf16 v[68:71], v[148:151], v[210:213], v[68:71]
	v_mfma_f32_16x16x32_bf16 v[64:67], v[156:159], v[210:213], v[64:67]
	s_setprio 0
	s_barrier
	s_add_i32 s34, s56, s37
	v_lshl_add_u64 v[188:189], v[188:189], 0, s[12:13]
	s_mov_b32 m0, s34
	ds_read_b128 v[172:175], v196 offset:49152
	ds_read_b128 v[176:179], v196 offset:50176
	ds_read_b128 v[180:183], v196 offset:51200
	ds_read_b128 v[184:187], v196 offset:52224
	ds_read_b128 v[198:201], v196 offset:53248
	ds_read_b128 v[202:205], v196 offset:54272
	ds_read_b128 v[206:209], v196 offset:55296
	ds_read_b128 v[210:213], v196 offset:56320
	global_load_lds_dwordx4 v[188:189], off
	s_add_i32 m0, s34, 0x2000
	s_add_u32 s30, s30, 0x40080
	v_lshl_add_u64 v[188:189], v[214:215], 0, s[12:13]
	s_addc_u32 s31, s31, 0
	s_add_i32 s34, s57, s37
	global_load_lds_dwordx4 v[188:189], off
	v_lshl_add_u64 v[188:189], s[30:31], 0, v[160:161]
	s_mov_b32 m0, s34
	s_nop 0
	s_nop 0
	v_lshl_add_u64 v[188:189], s[30:31], 0, v[162:163]
	s_add_i32 m0, s34, 0x2000
	s_nop 0
	s_nop 0
	v_lshl_add_u64 v[188:189], v[216:217], 0, s[12:13]
	s_mov_b32 m0, s48
	s_nop 0
	global_load_lds_dwordx4 v[188:189], off
	v_lshl_add_u64 v[188:189], v[218:219], 0, s[12:13]
	s_mov_b32 m0, s49
	s_nop 0
	global_load_lds_dwordx4 v[188:189], off
	s_waitcnt vmcnt(6)
	s_waitcnt lgkmcnt(0)
	s_barrier
	s_setprio 1
	s_waitcnt lgkmcnt(0)
	v_mfma_f32_16x16x32_bf16 v[60:63], v[80:83], v[172:175], v[60:63]
	v_mfma_f32_16x16x32_bf16 v[56:59], v[88:91], v[172:175], v[56:59]
	v_mfma_f32_16x16x32_bf16 v[44:47], v[80:83], v[180:183], v[44:47]
	v_mfma_f32_16x16x32_bf16 v[40:43], v[88:91], v[180:183], v[40:43]
	v_mfma_f32_16x16x32_bf16 v[28:31], v[80:83], v[198:201], v[28:31]
	v_mfma_f32_16x16x32_bf16 v[24:27], v[88:91], v[198:201], v[24:27]
	v_mfma_f32_16x16x32_bf16 v[12:15], v[80:83], v[206:209], v[12:15]
	v_mfma_f32_16x16x32_bf16 v[8:11], v[88:91], v[206:209], v[8:11]
	v_mfma_f32_16x16x32_bf16 v[60:63], v[84:87], v[176:179], v[60:63]
	v_mfma_f32_16x16x32_bf16 v[56:59], v[96:99], v[176:179], v[56:59]
	v_mfma_f32_16x16x32_bf16 v[44:47], v[84:87], v[184:187], v[44:47]
	v_mfma_f32_16x16x32_bf16 v[40:43], v[96:99], v[184:187], v[40:43]
	v_mfma_f32_16x16x32_bf16 v[28:31], v[84:87], v[202:205], v[28:31]
	v_mfma_f32_16x16x32_bf16 v[24:27], v[96:99], v[202:205], v[24:27]
	v_mfma_f32_16x16x32_bf16 v[12:15], v[84:87], v[210:213], v[12:15]
	v_mfma_f32_16x16x32_bf16 v[8:11], v[96:99], v[210:213], v[8:11]
	s_setprio 0
	s_setprio 1
	v_mfma_f32_16x16x32_bf16 v[52:55], v[144:147], v[172:175], v[52:55]
	v_mfma_f32_16x16x32_bf16 v[48:51], v[152:155], v[172:175], v[48:51]
	v_mfma_f32_16x16x32_bf16 v[36:39], v[144:147], v[180:183], v[36:39]
	v_mfma_f32_16x16x32_bf16 v[32:35], v[152:155], v[180:183], v[32:35]
	v_mfma_f32_16x16x32_bf16 v[20:23], v[144:147], v[198:201], v[20:23]
	v_mfma_f32_16x16x32_bf16 v[16:19], v[152:155], v[198:201], v[16:19]
	v_mfma_f32_16x16x32_bf16 v[4:7], v[144:147], v[206:209], v[4:7]
	v_mfma_f32_16x16x32_bf16 v[0:3], v[152:155], v[206:209], v[0:3]
	v_mfma_f32_16x16x32_bf16 v[52:55], v[148:151], v[176:179], v[52:55]
	v_mfma_f32_16x16x32_bf16 v[48:51], v[156:159], v[176:179], v[48:51]
	v_mfma_f32_16x16x32_bf16 v[36:39], v[148:151], v[184:187], v[36:39]
	v_mfma_f32_16x16x32_bf16 v[32:35], v[156:159], v[184:187], v[32:35]
	v_mfma_f32_16x16x32_bf16 v[20:23], v[148:151], v[202:205], v[20:23]
	v_mfma_f32_16x16x32_bf16 v[16:19], v[156:159], v[202:205], v[16:19]
	v_mfma_f32_16x16x32_bf16 v[4:7], v[148:151], v[210:213], v[4:7]
	v_mfma_f32_16x16x32_bf16 v[0:3], v[156:159], v[210:213], v[0:3]
	s_setprio 0
	s_barrier
	s_add_i32 s55, s55, 2
	s_add_u32 s28, s28, 0x100
	s_addc_u32 s29, s29, 0
	s_add_u32 s53, s53, 0x100
	s_addc_u32 s54, s54, 0
	s_cmp_gt_u32 s55, 13
	s_cbranch_scc0 .LBB0_980
	s_and_b64 vcc, exec, s[14:15]
	s_cbranch_vccz .LBB0_983
	s_barrier

.LBB0_1152:
	s_add_u32 s98, s39, 0xaff80
	s_addc_u32 s99, s40, 0
	ds_read_b128 v[128:131], v179
	ds_read_b128 v[132:135], v179 offset:1024
	ds_read_b128 v[136:139], v179 offset:2048
	ds_read_b128 v[140:143], v179 offset:3072
	ds_read_b128 v[144:147], v180
	ds_read_b128 v[148:151], v180 offset:1024
	ds_read_b128 v[164:167], v180 offset:2048
	ds_read_b128 v[168:171], v180 offset:3072
	s_add_u32 s14, s12, 0xfff50080
	s_addc_u32 s15, s13, -1
	s_cmp_eq_u32 s41, 40
	s_cselect_b32 s17, s3, s15
	s_cselect_b32 s16, s2, s14
	s_cselect_b32 s15, s11, s40
	s_cselect_b32 s14, s10, s39
	v_lshl_add_u64 v[172:173], s[98:99], 0, v[152:153]
	s_add_i32 m0, s20, 0x1c000
	s_nop 0
	global_load_lds_dwordx4 v[172:173], off
	v_lshl_add_u64 v[172:173], s[98:99], 0, v[154:155]
	s_add_i32 m0, s20, 0x1e000
	s_nop 0
	global_load_lds_dwordx4 v[172:173], off
	v_lshl_add_u64 v[172:173], s[12:13], 0, v[156:157]
	s_add_i32 m0, s22, 0xc000
	ds_read_b128 v[182:185], v181
	ds_read_b128 v[186:189], v181 offset:1024
	ds_read_b128 v[190:193], v181 offset:2048
	ds_read_b128 v[194:197], v181 offset:3072
	ds_read_b128 v[198:201], v181 offset:4096
	ds_read_b128 v[202:205], v181 offset:5120
	ds_read_b128 v[206:209], v181 offset:6144
	ds_read_b128 v[210:213], v181 offset:7168
	global_load_lds_dwordx4 v[172:173], off
	v_lshl_add_u64 v[172:173], s[12:13], 0, v[158:159]
	s_add_i32 m0, s22, 0xe000
	s_nop 0
	global_load_lds_dwordx4 v[172:173], off
	s_waitcnt vmcnt(8)
	s_waitcnt lgkmcnt(0)
	s_barrier
	s_setprio 1
	s_waitcnt lgkmcnt(0)
	v_mfma_f32_16x16x32_bf16 v[124:127], v[128:131], v[182:185], v[124:127]
	v_mfma_f32_16x16x32_bf16 v[120:123], v[136:139], v[182:185], v[120:123]
	v_mfma_f32_16x16x32_bf16 v[116:119], v[128:131], v[190:193], v[116:119]
	v_mfma_f32_16x16x32_bf16 v[112:115], v[136:139], v[190:193], v[112:115]
	v_mfma_f32_16x16x32_bf16 v[100:103], v[128:131], v[198:201], v[100:103]
	v_mfma_f32_16x16x32_bf16 v[88:91], v[136:139], v[198:201], v[88:91]
	v_mfma_f32_16x16x32_bf16 v[84:87], v[128:131], v[206:209], v[84:87]
	v_mfma_f32_16x16x32_bf16 v[76:79], v[136:139], v[206:209], v[76:79]
	v_mfma_f32_16x16x32_bf16 v[124:127], v[132:135], v[186:189], v[124:127]
	v_mfma_f32_16x16x32_bf16 v[120:123], v[140:143], v[186:189], v[120:123]
	v_mfma_f32_16x16x32_bf16 v[116:119], v[132:135], v[194:197], v[116:119]
	v_mfma_f32_16x16x32_bf16 v[112:115], v[140:143], v[194:197], v[112:115]
	v_mfma_f32_16x16x32_bf16 v[100:103], v[132:135], v[202:205], v[100:103]
	v_mfma_f32_16x16x32_bf16 v[88:91], v[140:143], v[202:205], v[88:91]
	v_mfma_f32_16x16x32_bf16 v[84:87], v[132:135], v[210:213], v[84:87]
	v_mfma_f32_16x16x32_bf16 v[76:79], v[140:143], v[210:213], v[76:79]
	s_setprio 0
	s_setprio 1
	v_mfma_f32_16x16x32_bf16 v[108:111], v[144:147], v[182:185], v[108:111]
	v_mfma_f32_16x16x32_bf16 v[104:107], v[164:167], v[182:185], v[104:107]
	v_mfma_f32_16x16x32_bf16 v[96:99], v[144:147], v[190:193], v[96:99]
	v_mfma_f32_16x16x32_bf16 v[92:95], v[164:167], v[190:193], v[92:95]
	v_mfma_f32_16x16x32_bf16 v[80:83], v[144:147], v[198:201], v[80:83]
	v_mfma_f32_16x16x32_bf16 v[72:75], v[164:167], v[198:201], v[72:75]
	v_mfma_f32_16x16x32_bf16 v[68:71], v[144:147], v[206:209], v[68:71]
	v_mfma_f32_16x16x32_bf16 v[64:67], v[164:167], v[206:209], v[64:67]
	v_mfma_f32_16x16x32_bf16 v[108:111], v[148:151], v[186:189], v[108:111]
	v_mfma_f32_16x16x32_bf16 v[104:107], v[168:171], v[186:189], v[104:107]
	v_mfma_f32_16x16x32_bf16 v[96:99], v[148:151], v[194:197], v[96:99]
	v_mfma_f32_16x16x32_bf16 v[92:95], v[168:171], v[194:197], v[92:95]
	v_mfma_f32_16x16x32_bf16 v[80:83], v[148:151], v[202:205], v[80:83]
	v_mfma_f32_16x16x32_bf16 v[72:75], v[168:171], v[202:205], v[72:75]
	v_mfma_f32_16x16x32_bf16 v[68:71], v[148:151], v[210:213], v[68:71]
	v_mfma_f32_16x16x32_bf16 v[64:67], v[168:171], v[210:213], v[64:67]
	s_setprio 0
	s_barrier
	s_add_i32 s42, s33, s20
	v_lshl_add_u64 v[172:173], s[14:15], 0, v[152:153]
	s_mov_b32 m0, s42
	ds_read_b128 v[182:185], v181 offset:16384
	ds_read_b128 v[186:189], v181 offset:17408
	ds_read_b128 v[190:193], v181 offset:18432
	ds_read_b128 v[194:197], v181 offset:19456
	ds_read_b128 v[198:201], v181 offset:20480
	ds_read_b128 v[202:205], v181 offset:21504
	ds_read_b128 v[206:209], v181 offset:22528
	ds_read_b128 v[210:213], v181 offset:23552
	global_load_lds_dwordx4 v[172:173], off
	s_add_i32 m0, s42, 0x2000
	s_add_u32 s42, s14, 0xb0000
	v_lshl_add_u64 v[214:215], s[14:15], 0, v[154:155]
	s_addc_u32 s43, s15, 0
	s_add_i32 s44, s34, s20
	global_load_lds_dwordx4 v[214:215], off
	v_lshl_add_u64 v[216:217], s[42:43], 0, v[152:153]
	s_mov_b32 m0, s44
	v_lshl_add_u64 v[218:219], s[16:17], 0, v[154:155]
	s_nop 0
	v_lshl_add_u64 v[216:217], s[42:43], 0, v[154:155]
	s_add_i32 m0, s44, 0x2000
	s_nop 0
	s_nop 0
	v_lshl_add_u64 v[216:217], s[16:17], 0, v[152:153]
	s_mov_b32 m0, s22
	s_nop 0
	global_load_lds_dwordx4 v[216:217], off
	s_mov_b32 m0, s23
	s_nop 0
	global_load_lds_dwordx4 v[218:219], off
	s_waitcnt vmcnt(6)
	s_waitcnt lgkmcnt(0)
	s_barrier
	s_setprio 1
	s_waitcnt lgkmcnt(0)
	v_mfma_f32_16x16x32_bf16 v[60:63], v[128:131], v[182:185], v[60:63]
	v_mfma_f32_16x16x32_bf16 v[56:59], v[136:139], v[182:185], v[56:59]
	v_mfma_f32_16x16x32_bf16 v[52:55], v[128:131], v[190:193], v[52:55]
	v_mfma_f32_16x16x32_bf16 v[48:51], v[136:139], v[190:193], v[48:51]
	v_mfma_f32_16x16x32_bf16 v[40:43], v[128:131], v[198:201], v[40:43]
	v_mfma_f32_16x16x32_bf16 v[28:31], v[136:139], v[198:201], v[28:31]
	v_mfma_f32_16x16x32_bf16 v[16:19], v[128:131], v[206:209], v[16:19]
	v_mfma_f32_16x16x32_bf16 v[8:11], v[136:139], v[206:209], v[8:11]
	v_mfma_f32_16x16x32_bf16 v[60:63], v[132:135], v[186:189], v[60:63]
	v_mfma_f32_16x16x32_bf16 v[56:59], v[140:143], v[186:189], v[56:59]
	v_mfma_f32_16x16x32_bf16 v[52:55], v[132:135], v[194:197], v[52:55]
	v_mfma_f32_16x16x32_bf16 v[48:51], v[140:143], v[194:197], v[48:51]
	v_mfma_f32_16x16x32_bf16 v[40:43], v[132:135], v[202:205], v[40:43]
	v_mfma_f32_16x16x32_bf16 v[28:31], v[140:143], v[202:205], v[28:31]
	v_mfma_f32_16x16x32_bf16 v[16:19], v[132:135], v[210:213], v[16:19]
	v_mfma_f32_16x16x32_bf16 v[8:11], v[140:143], v[210:213], v[8:11]
	s_setprio 0
	s_setprio 1
	v_mfma_f32_16x16x32_bf16 v[44:47], v[144:147], v[182:185], v[44:47]
	v_mfma_f32_16x16x32_bf16 v[36:39], v[164:167], v[182:185], v[36:39]
	v_mfma_f32_16x16x32_bf16 v[32:35], v[144:147], v[190:193], v[32:35]
	v_mfma_f32_16x16x32_bf16 v[24:27], v[164:167], v[190:193], v[24:27]
	v_mfma_f32_16x16x32_bf16 v[20:23], v[144:147], v[198:201], v[20:23]
	v_mfma_f32_16x16x32_bf16 v[12:15], v[164:167], v[198:201], v[12:15]
	v_mfma_f32_16x16x32_bf16 v[4:7], v[144:147], v[206:209], v[4:7]
	v_mfma_f32_16x16x32_bf16 v[0:3], v[164:167], v[206:209], v[0:3]
	v_mfma_f32_16x16x32_bf16 v[44:47], v[148:151], v[186:189], v[44:47]
	v_mfma_f32_16x16x32_bf16 v[36:39], v[168:171], v[186:189], v[36:39]
	v_mfma_f32_16x16x32_bf16 v[32:35], v[148:151], v[194:197], v[32:35]
	v_mfma_f32_16x16x32_bf16 v[24:27], v[168:171], v[194:197], v[24:27]
	v_mfma_f32_16x16x32_bf16 v[20:23], v[148:151], v[202:205], v[20:23]
	v_mfma_f32_16x16x32_bf16 v[12:15], v[168:171], v[202:205], v[12:15]
	v_mfma_f32_16x16x32_bf16 v[4:7], v[148:151], v[210:213], v[4:7]
	v_mfma_f32_16x16x32_bf16 v[0:3], v[168:171], v[210:213], v[0:3]
	s_setprio 0
	s_barrier
	s_add_u32 s98, s14, 0xb0000
	s_addc_u32 s99, s15, 0
	s_add_i32 s42, 0, 0x18000
	s_add_i32 s43, 0, 0x1c000
	v_add_u32_e32 v140, s42, v175
	v_add_u32_e32 v168, s43, v175
	ds_read_b128 v[128:131], v140
	ds_read_b128 v[132:135], v140 offset:1024
	ds_read_b128 v[136:139], v140 offset:2048
	ds_read_b128 v[140:143], v140 offset:3072
	ds_read_b128 v[144:147], v168
	ds_read_b128 v[148:151], v168 offset:1024
	ds_read_b128 v[164:167], v168 offset:2048
	ds_read_b128 v[168:171], v168 offset:3072
	s_add_u32 s16, s16, 0xb0000
	s_addc_u32 s17, s17, 0
	s_mov_b32 m0, s24
	v_lshl_add_u64 v[220:221], s[98:99], 0, v[152:153]
	s_add_i32 s100, s34, s20
	s_mov_b32 m0, s100
	s_nop 0
	global_load_lds_dwordx4 v[220:221], off
	v_lshl_add_u64 v[220:221], s[98:99], 0, v[154:155]
	s_add_i32 m0, s100, 0x2000
	s_nop 0
	global_load_lds_dwordx4 v[220:221], off
	s_mov_b32 m0, s24
	s_nop 0
	v_lshl_add_u64 v[220:221], s[16:17], 0, v[152:153]
	ds_read_b128 v[182:185], v181 offset:32768
	ds_read_b128 v[186:189], v181 offset:33792
	ds_read_b128 v[190:193], v181 offset:34816
	ds_read_b128 v[194:197], v181 offset:35840
	ds_read_b128 v[198:201], v181 offset:36864
	ds_read_b128 v[202:205], v181 offset:37888
	ds_read_b128 v[206:209], v181 offset:38912
	ds_read_b128 v[210:213], v181 offset:39936
	global_load_lds_dwordx4 v[220:221], off
	v_lshl_add_u64 v[220:221], s[16:17], 0, v[154:155]
	s_mov_b32 m0, s25
	s_nop 0
	global_load_lds_dwordx4 v[220:221], off
	s_waitcnt vmcnt(8)
	s_waitcnt lgkmcnt(0)
	s_barrier
	s_setprio 1
	s_waitcnt lgkmcnt(0)
	v_mfma_f32_16x16x32_bf16 v[124:127], v[128:131], v[182:185], v[124:127]
	v_mfma_f32_16x16x32_bf16 v[120:123], v[136:139], v[182:185], v[120:123]
	v_mfma_f32_16x16x32_bf16 v[116:119], v[128:131], v[190:193], v[116:119]
	v_mfma_f32_16x16x32_bf16 v[112:115], v[136:139], v[190:193], v[112:115]
	v_mfma_f32_16x16x32_bf16 v[100:103], v[128:131], v[198:201], v[100:103]
	v_mfma_f32_16x16x32_bf16 v[88:91], v[136:139], v[198:201], v[88:91]
	v_mfma_f32_16x16x32_bf16 v[84:87], v[128:131], v[206:209], v[84:87]
	v_mfma_f32_16x16x32_bf16 v[76:79], v[136:139], v[206:209], v[76:79]
	v_mfma_f32_16x16x32_bf16 v[124:127], v[132:135], v[186:189], v[124:127]
	v_mfma_f32_16x16x32_bf16 v[120:123], v[140:143], v[186:189], v[120:123]
	v_mfma_f32_16x16x32_bf16 v[116:119], v[132:135], v[194:197], v[116:119]
	v_mfma_f32_16x16x32_bf16 v[112:115], v[140:143], v[194:197], v[112:115]
	v_mfma_f32_16x16x32_bf16 v[100:103], v[132:135], v[202:205], v[100:103]
	v_mfma_f32_16x16x32_bf16 v[88:91], v[140:143], v[202:205], v[88:91]
	v_mfma_f32_16x16x32_bf16 v[84:87], v[132:135], v[210:213], v[84:87]
	v_mfma_f32_16x16x32_bf16 v[76:79], v[140:143], v[210:213], v[76:79]
	s_setprio 0
	s_setprio 1
	v_mfma_f32_16x16x32_bf16 v[108:111], v[144:147], v[182:185], v[108:111]
	v_mfma_f32_16x16x32_bf16 v[104:107], v[164:167], v[182:185], v[104:107]
	v_mfma_f32_16x16x32_bf16 v[96:99], v[144:147], v[190:193], v[96:99]
	v_mfma_f32_16x16x32_bf16 v[92:95], v[164:167], v[190:193], v[92:95]
	v_mfma_f32_16x16x32_bf16 v[80:83], v[144:147], v[198:201], v[80:83]
	v_mfma_f32_16x16x32_bf16 v[72:75], v[164:167], v[198:201], v[72:75]
	v_mfma_f32_16x16x32_bf16 v[68:71], v[144:147], v[206:209], v[68:71]
	v_mfma_f32_16x16x32_bf16 v[64:67], v[164:167], v[206:209], v[64:67]
	v_mfma_f32_16x16x32_bf16 v[108:111], v[148:151], v[186:189], v[108:111]
	v_mfma_f32_16x16x32_bf16 v[104:107], v[168:171], v[186:189], v[104:107]
	v_mfma_f32_16x16x32_bf16 v[96:99], v[148:151], v[194:197], v[96:99]
	v_mfma_f32_16x16x32_bf16 v[92:95], v[168:171], v[194:197], v[92:95]
	v_mfma_f32_16x16x32_bf16 v[80:83], v[148:151], v[202:205], v[80:83]
	v_mfma_f32_16x16x32_bf16 v[72:75], v[168:171], v[202:205], v[72:75]
	v_mfma_f32_16x16x32_bf16 v[68:71], v[148:151], v[210:213], v[68:71]
	v_mfma_f32_16x16x32_bf16 v[64:67], v[168:171], v[210:213], v[64:67]
	s_setprio 0
	s_barrier
	s_add_i32 s16, s42, s20
	v_lshl_add_u64 v[172:173], v[172:173], 0, s[6:7]
	s_mov_b32 m0, s16
	ds_read_b128 v[182:185], v181 offset:49152
	ds_read_b128 v[186:189], v181 offset:50176
	ds_read_b128 v[190:193], v181 offset:51200
	ds_read_b128 v[194:197], v181 offset:52224
	ds_read_b128 v[198:201], v181 offset:53248
	ds_read_b128 v[202:205], v181 offset:54272
	ds_read_b128 v[206:209], v181 offset:55296
	ds_read_b128 v[210:213], v181 offset:56320
	global_load_lds_dwordx4 v[172:173], off
	s_add_i32 m0, s16, 0x2000
	s_add_u32 s14, s14, 0xb0080
	v_lshl_add_u64 v[172:173], v[214:215], 0, s[6:7]
	s_addc_u32 s15, s15, 0
	s_add_i32 s16, s43, s20
	global_load_lds_dwordx4 v[172:173], off
	v_lshl_add_u64 v[172:173], s[14:15], 0, v[152:153]
	s_mov_b32 m0, s16
	s_nop 0
	s_nop 0
	v_lshl_add_u64 v[172:173], s[14:15], 0, v[154:155]
	s_add_i32 m0, s16, 0x2000
	s_nop 0
	s_nop 0
	v_lshl_add_u64 v[172:173], v[216:217], 0, s[6:7]
	s_mov_b32 m0, s30
	s_nop 0
	global_load_lds_dwordx4 v[172:173], off
	v_lshl_add_u64 v[172:173], v[218:219], 0, s[6:7]
	s_mov_b32 m0, s31
	s_nop 0
	global_load_lds_dwordx4 v[172:173], off
	s_waitcnt vmcnt(6)
	s_waitcnt lgkmcnt(0)
	s_barrier
	s_setprio 1
	s_waitcnt lgkmcnt(0)
	v_mfma_f32_16x16x32_bf16 v[60:63], v[128:131], v[182:185], v[60:63]
	v_mfma_f32_16x16x32_bf16 v[56:59], v[136:139], v[182:185], v[56:59]
	v_mfma_f32_16x16x32_bf16 v[52:55], v[128:131], v[190:193], v[52:55]
	v_mfma_f32_16x16x32_bf16 v[48:51], v[136:139], v[190:193], v[48:51]
	v_mfma_f32_16x16x32_bf16 v[40:43], v[128:131], v[198:201], v[40:43]
	v_mfma_f32_16x16x32_bf16 v[28:31], v[136:139], v[198:201], v[28:31]
	v_mfma_f32_16x16x32_bf16 v[16:19], v[128:131], v[206:209], v[16:19]
	v_mfma_f32_16x16x32_bf16 v[8:11], v[136:139], v[206:209], v[8:11]
	v_mfma_f32_16x16x32_bf16 v[60:63], v[132:135], v[186:189], v[60:63]
	v_mfma_f32_16x16x32_bf16 v[56:59], v[140:143], v[186:189], v[56:59]
	v_mfma_f32_16x16x32_bf16 v[52:55], v[132:135], v[194:197], v[52:55]
	v_mfma_f32_16x16x32_bf16 v[48:51], v[140:143], v[194:197], v[48:51]
	v_mfma_f32_16x16x32_bf16 v[40:43], v[132:135], v[202:205], v[40:43]
	v_mfma_f32_16x16x32_bf16 v[28:31], v[140:143], v[202:205], v[28:31]
	v_mfma_f32_16x16x32_bf16 v[16:19], v[132:135], v[210:213], v[16:19]
	v_mfma_f32_16x16x32_bf16 v[8:11], v[140:143], v[210:213], v[8:11]
	s_setprio 0
	s_setprio 1
	v_mfma_f32_16x16x32_bf16 v[44:47], v[144:147], v[182:185], v[44:47]
	v_mfma_f32_16x16x32_bf16 v[36:39], v[164:167], v[182:185], v[36:39]
	v_mfma_f32_16x16x32_bf16 v[32:35], v[144:147], v[190:193], v[32:35]
	v_mfma_f32_16x16x32_bf16 v[24:27], v[164:167], v[190:193], v[24:27]
	v_mfma_f32_16x16x32_bf16 v[20:23], v[144:147], v[198:201], v[20:23]
	v_mfma_f32_16x16x32_bf16 v[12:15], v[164:167], v[198:201], v[12:15]
	v_mfma_f32_16x16x32_bf16 v[4:7], v[144:147], v[206:209], v[4:7]
	v_mfma_f32_16x16x32_bf16 v[0:3], v[164:167], v[206:209], v[0:3]
	v_mfma_f32_16x16x32_bf16 v[44:47], v[148:151], v[186:189], v[44:47]
	v_mfma_f32_16x16x32_bf16 v[36:39], v[168:171], v[186:189], v[36:39]
	v_mfma_f32_16x16x32_bf16 v[32:35], v[148:151], v[194:197], v[32:35]
	v_mfma_f32_16x16x32_bf16 v[24:27], v[168:171], v[194:197], v[24:27]
	v_mfma_f32_16x16x32_bf16 v[20:23], v[148:151], v[202:205], v[20:23]
	v_mfma_f32_16x16x32_bf16 v[12:15], v[168:171], v[202:205], v[12:15]
	v_mfma_f32_16x16x32_bf16 v[4:7], v[148:151], v[210:213], v[4:7]
	v_mfma_f32_16x16x32_bf16 v[0:3], v[168:171], v[210:213], v[0:3]
	s_setprio 0
	s_barrier
	s_add_i32 s41, s41, 2
	s_add_u32 s12, s12, 0x100
	s_addc_u32 s13, s13, 0
	s_add_u32 s39, s39, 0x100
	s_addc_u32 s40, s40, 0
	s_cmp_gt_u32 s41, 41
	s_cbranch_scc0 .LBB0_1152
	s_and_b64 vcc, exec, s[8:9]
	s_cbranch_vccz .LBB0_1155
	s_barrier

	.amdhsa_kernel _Z8yoco_fwd4Args
		.amdhsa_group_segment_fixed_size 0
		.amdhsa_private_segment_fixed_size 0
		.amdhsa_kernarg_size 432
		.amdhsa_user_sgpr_count 2
		.amdhsa_user_sgpr_dispatch_ptr 0
		.amdhsa_user_sgpr_queue_ptr 0
		.amdhsa_user_sgpr_kernarg_segment_ptr 1
		.amdhsa_user_sgpr_dispatch_id 0
		.amdhsa_user_sgpr_kernarg_preload_length 0
		.amdhsa_user_sgpr_kernarg_preload_offset 0
		.amdhsa_user_sgpr_private_segment_size 0
		.amdhsa_uses_dynamic_stack 0
		.amdhsa_enable_private_segment 0
		.amdhsa_system_sgpr_workgroup_id_x 1
		.amdhsa_system_sgpr_workgroup_id_y 0
		.amdhsa_system_sgpr_workgroup_id_z 0
		.amdhsa_system_sgpr_workgroup_info 0
		.amdhsa_system_vgpr_workitem_id 2
		.amdhsa_next_free_vgpr 256
		.amdhsa_next_free_sgpr 102
		.amdhsa_accum_offset 256
		.amdhsa_reserve_vcc 1
		.amdhsa_float_round_mode_32 0
		.amdhsa_float_round_mode_16_64 0
		.amdhsa_float_denorm_mode_32 3
		.amdhsa_float_denorm_mode_16_64 3
		.amdhsa_dx10_clamp 1
		.amdhsa_ieee_mode 1
		.amdhsa_fp16_overflow 0
		.amdhsa_tg_split 0
		.amdhsa_exception_fp_ieee_invalid_op 0
		.amdhsa_exception_fp_denorm_src 0
		.amdhsa_exception_fp_ieee_div_zero 0
		.amdhsa_exception_fp_ieee_overflow 0
		.amdhsa_exception_fp_ieee_underflow 0
		.amdhsa_exception_fp_ieee_inexact 0
		.amdhsa_exception_int_div_zero 0
	.end_amdhsa_kernel

amdhsa.kernels:
  - .agpr_count:     0
    .args:
      - .offset:         0
        .size:           176
        .value_kind:     by_value
      - .offset:         176
        .size:           4
        .value_kind:     hidden_block_count_x
      - .offset:         180
        .size:           4
        .value_kind:     hidden_block_count_y
      - .offset:         184
        .size:           4
        .value_kind:     hidden_block_count_z
      - .offset:         188
        .size:           2
        .value_kind:     hidden_group_size_x
      - .offset:         190
        .size:           2
        .value_kind:     hidden_group_size_y
      - .offset:         192
        .size:           2
        .value_kind:     hidden_group_size_z
      - .offset:         194
        .size:           2
        .value_kind:     hidden_remainder_x
      - .offset:         196
        .size:           2
        .value_kind:     hidden_remainder_y
      - .offset:         198
        .size:           2
        .value_kind:     hidden_remainder_z
      - .offset:         216
        .size:           8
        .value_kind:     hidden_global_offset_x
      - .offset:         224
        .size:           8
        .value_kind:     hidden_global_offset_y
      - .offset:         232
        .size:           8
        .value_kind:     hidden_global_offset_z
      - .offset:         240
        .size:           2
        .value_kind:     hidden_grid_dims
      - .offset:         264
        .size:           8
        .value_kind:     hidden_multigrid_sync_arg
      - .offset:         296
        .size:           4
        .value_kind:     hidden_dynamic_lds_size
    .group_segment_fixed_size: 0
    .kernarg_segment_align: 8
    .kernarg_segment_size: 432
    .language:       OpenCL C
    .language_version:
      - 2
      - 0
    .max_flat_workgroup_size: 512
    .name:           _Z8yoco_fwd4Args
    .private_segment_fixed_size: 0
    .sgpr_count:     108
    .sgpr_spill_count: 203
    .symbol:         _Z8yoco_fwd4Args.kd
    .uniform_work_group_size: 1
    .uses_dynamic_stack: false
    .vgpr_count:     256
    .vgpr_spill_count: 0
    .wavefront_size: 64
